# v45 with s_setprio 1 issued before the barrier that opens each MFMA cluster in the six GEMM main loops
# baseline (speedup 1.0000x reference)
; #define PG8_STAGE(bufoff, gbase, voff) do { _Pragma("unroll") for (int _i = 0; _i < 2; ++_i) \
;         __builtin_amdgcn_global_load_lds((const unsigned*)((const char*)(gbase) + (voff)[_i]), (LAS unsigned*)(lds + (bufoff) + ldsw + _i * 8192), 16, 0, 0); } while (0)
; #define PG8_LDA(dst, b, h) do { _Pragma("unroll") for (int m = 0; m < 4; ++m) _Pragma("unroll") for (int k = 0; k < 2; ++k) dst[m][k] = *(const LAS bf16x8*)(lds + PG8_SA(b, h) + aoff + m * 2048 + k * 1024); } while (0)
; #define PG8_LDB(dst, b, h) do { _Pragma("unroll") for (int n = 0; n < 2; ++n) _Pragma("unroll") for (int k = 0; k < 2; ++k) dst[n][k] = *(const LAS bf16x8*)(lds + PG8_SB(b, h) + boff + n * 2048 + k * 1024); } while (0)
; #define PG8_MMA(ai, bj, At, Bt) do { __builtin_amdgcn_s_setprio(1); _Pragma("unroll") for (int m = 0; m < 4; ++m) _Pragma("unroll") for (int n = 0; n < 2; ++n) _Pragma("unroll") for (int k = 0; k < 2; ++k) \
;         acc[ai][bj][m][n] = __builtin_amdgcn_mfma_f32_16x16x32_bf16(Bt[n][k], At[m][k], acc[ai][bj][m][n], 0, 0, 0); __builtin_amdgcn_s_setprio(0); } while (0)
; #define PG8_WAIT_V(n) asm volatile("s_waitcnt vmcnt(" #n ")" ::: "memory")
; #define PG8_WAIT_L(n) asm volatile("s_waitcnt lgkmcnt(" #n ")" ::: "memory")
; #define PG8_BAR __builtin_amdgcn_s_barrier()
; #define PG8_SCHED __builtin_amdgcn_sched_barrier(0)
; template <class Epi, class Sched>
; __device__ __forceinline__ void gemm_phase(LAS unsigned char* lds, const int K, const Sched& S, const Epi& E) {
;     ...
;         for (int t = 0; t < nt; t += 2) {
;             const bool last = (t == nt - 2);
;             const char* a1 = cA + (size_t)(t + 1) * kstep;
;             const char* a2 = last ? nA : cA + (size_t)(t + 2) * kstep; const char* b2 = last ? nB : cB + (size_t)(t + 2) * kstep;
;             const char* a3 = a2 + kstep; const char* b3 = b2 + kstep;
;             PG8_LDB(B0, 0, 0); PG8_LDB(B1, 0, 1); PG8_SCHED; PG8_LDA(At, 0, 0); PG8_STAGE(PG8_SA(1, 1), a1 + hstep, voffA);
;             PG8_WAIT_V(8); PG8_WAIT_L(0); PG8_BAR; PG8_MMA(0, 0, At, B0); PG8_MMA(0, 1, At, B1); PG8_BAR; PG8_SCHED;
;             PG8_LDA(At, 0, 1); PG8_STAGE(PG8_SB(0, 0), b2, voffB); PG8_STAGE(PG8_SB(0, 1), b2 + hstep, voffB); PG8_STAGE(PG8_SA(0, 0), a2, voffA);
;             PG8_WAIT_V(8); PG8_WAIT_L(0); PG8_BAR; PG8_MMA(1, 0, At, B0); PG8_MMA(1, 1, At, B1); PG8_BAR; PG8_SCHED;
.LBB0_485:
	ds_read_b128 v[140:143], v147
	ds_read_b128 v[150:153], v147 offset:1024
	ds_read_b128 v[154:157], v147 offset:2048
	ds_read_b128 v[158:161], v147 offset:3072
	ds_read_b128 v[162:165], v148
	ds_read_b128 v[170:173], v148 offset:1024
	ds_read_b128 v[174:177], v148 offset:2048
	ds_read_b128 v[178:181], v148 offset:3072
	s_add_u32 s19, s34, 0xfff80080
	s_addc_u32 s38, s35, -1
	s_cmp_eq_u32 s17, 28
	s_cselect_b32 s41, s23, s38
	s_cselect_b32 s40, s22, s19
	s_cselect_b32 s39, s25, s9
	s_cselect_b32 s38, s24, s8
	s_mov_b32 m0, s50
	v_lshl_add_u64 v[166:167], s[34:35], 0, v[136:137]
	ds_read_b128 v[182:185], v149
	ds_read_b128 v[186:189], v149 offset:1024
	ds_read_b128 v[190:193], v149 offset:2048
	ds_read_b128 v[194:197], v149 offset:3072
	ds_read_b128 v[198:201], v149 offset:4096
	ds_read_b128 v[202:205], v149 offset:5120
	ds_read_b128 v[206:209], v149 offset:6144
	ds_read_b128 v[210:213], v149 offset:7168
	global_load_lds_dwordx4 v[166:167], off
	v_lshl_add_u64 v[166:167], s[34:35], 0, v[138:139]
	s_mov_b32 m0, s51
	s_nop 0
	global_load_lds_dwordx4 v[166:167], off
	s_waitcnt vmcnt(8)
	s_waitcnt lgkmcnt(0)
	s_setprio 1
	s_barrier
	v_mfma_f32_16x16x32_bf16 v[124:127], v[140:143], v[182:185], v[124:127]
	v_mfma_f32_16x16x32_bf16 v[120:123], v[154:157], v[182:185], v[120:123]
	v_mfma_f32_16x16x32_bf16 v[108:111], v[140:143], v[190:193], v[108:111]
	v_mfma_f32_16x16x32_bf16 v[104:107], v[154:157], v[190:193], v[104:107]
	v_mfma_f32_16x16x32_bf16 v[92:95], v[140:143], v[198:201], v[92:95]
	v_mfma_f32_16x16x32_bf16 v[88:91], v[154:157], v[198:201], v[88:91]
	v_mfma_f32_16x16x32_bf16 v[76:79], v[140:143], v[206:209], v[76:79]
	v_mfma_f32_16x16x32_bf16 v[72:75], v[154:157], v[206:209], v[72:75]
	v_mfma_f32_16x16x32_bf16 v[124:127], v[150:153], v[186:189], v[124:127]
	v_mfma_f32_16x16x32_bf16 v[120:123], v[158:161], v[186:189], v[120:123]
	v_mfma_f32_16x16x32_bf16 v[108:111], v[150:153], v[194:197], v[108:111]
	v_mfma_f32_16x16x32_bf16 v[104:107], v[158:161], v[194:197], v[104:107]
	v_mfma_f32_16x16x32_bf16 v[92:95], v[150:153], v[202:205], v[92:95]
	v_mfma_f32_16x16x32_bf16 v[88:91], v[158:161], v[202:205], v[88:91]
	v_mfma_f32_16x16x32_bf16 v[76:79], v[150:153], v[210:213], v[76:79]
	v_mfma_f32_16x16x32_bf16 v[72:75], v[158:161], v[210:213], v[72:75]
	v_mfma_f32_16x16x32_bf16 v[116:119], v[162:165], v[182:185], v[116:119]
	v_mfma_f32_16x16x32_bf16 v[112:115], v[174:177], v[182:185], v[112:115]
	v_mfma_f32_16x16x32_bf16 v[100:103], v[162:165], v[190:193], v[100:103]
	v_mfma_f32_16x16x32_bf16 v[96:99], v[174:177], v[190:193], v[96:99]
	v_mfma_f32_16x16x32_bf16 v[84:87], v[162:165], v[198:201], v[84:87]
	v_mfma_f32_16x16x32_bf16 v[80:83], v[174:177], v[198:201], v[80:83]
	v_mfma_f32_16x16x32_bf16 v[68:71], v[162:165], v[206:209], v[68:71]
	v_mfma_f32_16x16x32_bf16 v[64:67], v[174:177], v[206:209], v[64:67]
	v_mfma_f32_16x16x32_bf16 v[116:119], v[170:173], v[186:189], v[116:119]
	v_mfma_f32_16x16x32_bf16 v[112:115], v[178:181], v[186:189], v[112:115]
	v_mfma_f32_16x16x32_bf16 v[100:103], v[170:173], v[194:197], v[100:103]
	v_mfma_f32_16x16x32_bf16 v[96:99], v[178:181], v[194:197], v[96:99]
	v_mfma_f32_16x16x32_bf16 v[84:87], v[170:173], v[202:205], v[84:87]
	v_mfma_f32_16x16x32_bf16 v[80:83], v[178:181], v[202:205], v[80:83]
	v_mfma_f32_16x16x32_bf16 v[68:71], v[170:173], v[210:213], v[68:71]
	v_mfma_f32_16x16x32_bf16 v[64:67], v[178:181], v[210:213], v[64:67]
	s_setprio 0
	s_barrier
	s_mov_b32 m0, s68
	v_lshl_add_u64 v[166:167], s[38:39], 0, v[130:131]
	ds_read_b128 v[182:185], v149 offset:16384
	ds_read_b128 v[186:189], v149 offset:17408
	ds_read_b128 v[190:193], v149 offset:18432
	ds_read_b128 v[194:197], v149 offset:19456
	ds_read_b128 v[198:201], v149 offset:20480
	ds_read_b128 v[202:205], v149 offset:21504
	ds_read_b128 v[206:209], v149 offset:22528
	ds_read_b128 v[210:213], v149 offset:23552
	global_load_lds_dwordx4 v[166:167], off
	s_add_i32 m0, s68, 0x2000
	s_add_u32 s70, s38, 0x80000
	v_lshl_add_u64 v[214:215], s[38:39], 0, v[134:135]
	s_addc_u32 s71, s39, 0
	s_add_i32 s19, s48, s36
	global_load_lds_dwordx4 v[214:215], off
	v_lshl_add_u64 v[216:217], s[70:71], 0, v[130:131]
	s_mov_b32 m0, s19
	v_lshl_add_u64 v[218:219], s[40:41], 0, v[132:133]
	global_load_lds_dwordx4 v[216:217], off
	v_lshl_add_u64 v[216:217], s[70:71], 0, v[134:135]
	s_add_i32 m0, s19, 0x2000
	s_nop 0
	global_load_lds_dwordx4 v[216:217], off
	v_lshl_add_u64 v[216:217], s[40:41], 0, v[128:129]
	s_mov_b32 m0, s31
	s_nop 0
	global_load_lds_dwordx4 v[216:217], off
	s_mov_b32 m0, s42
	s_nop 0
	global_load_lds_dwordx4 v[218:219], off
	s_waitcnt vmcnt(8)
	s_waitcnt lgkmcnt(0)
	s_setprio 1
	s_barrier
; #define PG8_STAGE(bufoff, gbase, voff) do { _Pragma("unroll") for (int _i = 0; _i < 2; ++_i) \
;         __builtin_amdgcn_global_load_lds((const unsigned*)((const char*)(gbase) + (voff)[_i]), (LAS unsigned*)(lds + (bufoff) + ldsw + _i * 8192), 16, 0, 0); } while (0)
; #define PG8_LDA(dst, b, h) do { _Pragma("unroll") for (int m = 0; m < 4; ++m) _Pragma("unroll") for (int k = 0; k < 2; ++k) dst[m][k] = *(const LAS bf16x8*)(lds + PG8_SA(b, h) + aoff + m * 2048 + k * 1024); } while (0)
; #define PG8_LDB(dst, b, h) do { _Pragma("unroll") for (int n = 0; n < 2; ++n) _Pragma("unroll") for (int k = 0; k < 2; ++k) dst[n][k] = *(const LAS bf16x8*)(lds + PG8_SB(b, h) + boff + n * 2048 + k * 1024); } while (0)
; #define PG8_MMA(ai, bj, At, Bt) do { __builtin_amdgcn_s_setprio(1); _Pragma("unroll") for (int m = 0; m < 4; ++m) _Pragma("unroll") for (int n = 0; n < 2; ++n) _Pragma("unroll") for (int k = 0; k < 2; ++k) \
;         acc[ai][bj][m][n] = __builtin_amdgcn_mfma_f32_16x16x32_bf16(Bt[n][k], At[m][k], acc[ai][bj][m][n], 0, 0, 0); __builtin_amdgcn_s_setprio(0); } while (0)
; #define PG8_WAIT_V(n) asm volatile("s_waitcnt vmcnt(" #n ")" ::: "memory")
; #define PG8_WAIT_L(n) asm volatile("s_waitcnt lgkmcnt(" #n ")" ::: "memory")
; #define PG8_BAR __builtin_amdgcn_s_barrier()
; #define PG8_SCHED __builtin_amdgcn_sched_barrier(0)
; template <class Epi, class Sched>
; __device__ __forceinline__ void gemm_phase(LAS unsigned char* lds, const int K, const Sched& S, const Epi& E) {
;     ...
;             PG8_WAIT_V(8); PG8_WAIT_L(0); PG8_BAR; PG8_MMA(1, 0, At, B0); PG8_MMA(1, 1, At, B1); PG8_BAR; PG8_SCHED;
;             PG8_LDB(B0, 1, 0); PG8_LDB(B1, 1, 1); PG8_SCHED; PG8_LDA(At, 1, 0); PG8_STAGE(PG8_SA(0, 1), a2 + hstep, voffA);
;             PG8_WAIT_V(8); PG8_WAIT_L(0); PG8_BAR; PG8_MMA(0, 0, At, B0); PG8_MMA(0, 1, At, B1); PG8_BAR; PG8_SCHED;
	v_mfma_f32_16x16x32_bf16 v[60:63], v[140:143], v[182:185], v[60:63]
	v_mfma_f32_16x16x32_bf16 v[56:59], v[154:157], v[182:185], v[56:59]
	v_mfma_f32_16x16x32_bf16 v[44:47], v[140:143], v[190:193], v[44:47]
	v_mfma_f32_16x16x32_bf16 v[40:43], v[154:157], v[190:193], v[40:43]
	v_mfma_f32_16x16x32_bf16 v[28:31], v[140:143], v[198:201], v[28:31]
	v_mfma_f32_16x16x32_bf16 v[24:27], v[154:157], v[198:201], v[24:27]
	v_mfma_f32_16x16x32_bf16 v[12:15], v[140:143], v[206:209], v[12:15]
	v_mfma_f32_16x16x32_bf16 v[8:11], v[154:157], v[206:209], v[8:11]
	v_mfma_f32_16x16x32_bf16 v[60:63], v[150:153], v[186:189], v[60:63]
	v_mfma_f32_16x16x32_bf16 v[56:59], v[158:161], v[186:189], v[56:59]
	v_mfma_f32_16x16x32_bf16 v[44:47], v[150:153], v[194:197], v[44:47]
	v_mfma_f32_16x16x32_bf16 v[40:43], v[158:161], v[194:197], v[40:43]
	v_mfma_f32_16x16x32_bf16 v[28:31], v[150:153], v[202:205], v[28:31]
	v_mfma_f32_16x16x32_bf16 v[24:27], v[158:161], v[202:205], v[24:27]
	v_mfma_f32_16x16x32_bf16 v[12:15], v[150:153], v[210:213], v[12:15]
	v_mfma_f32_16x16x32_bf16 v[8:11], v[158:161], v[210:213], v[8:11]
	v_mfma_f32_16x16x32_bf16 v[52:55], v[162:165], v[182:185], v[52:55]
	v_mfma_f32_16x16x32_bf16 v[48:51], v[174:177], v[182:185], v[48:51]
	v_mfma_f32_16x16x32_bf16 v[36:39], v[162:165], v[190:193], v[36:39]
	v_mfma_f32_16x16x32_bf16 v[32:35], v[174:177], v[190:193], v[32:35]
	v_mfma_f32_16x16x32_bf16 v[20:23], v[162:165], v[198:201], v[20:23]
	v_mfma_f32_16x16x32_bf16 v[16:19], v[174:177], v[198:201], v[16:19]
	v_mfma_f32_16x16x32_bf16 v[4:7], v[162:165], v[206:209], v[4:7]
	v_mfma_f32_16x16x32_bf16 v[0:3], v[174:177], v[206:209], v[0:3]
	v_mfma_f32_16x16x32_bf16 v[52:55], v[170:173], v[186:189], v[52:55]
	v_mfma_f32_16x16x32_bf16 v[48:51], v[178:181], v[186:189], v[48:51]
	v_mfma_f32_16x16x32_bf16 v[36:39], v[170:173], v[194:197], v[36:39]
	v_mfma_f32_16x16x32_bf16 v[32:35], v[178:181], v[194:197], v[32:35]
	v_mfma_f32_16x16x32_bf16 v[20:23], v[170:173], v[202:205], v[20:23]
	v_mfma_f32_16x16x32_bf16 v[16:19], v[178:181], v[202:205], v[16:19]
	v_mfma_f32_16x16x32_bf16 v[4:7], v[170:173], v[210:213], v[4:7]
	v_mfma_f32_16x16x32_bf16 v[0:3], v[178:181], v[210:213], v[0:3]
	s_setprio 0
	s_barrier
	s_add_i32 s19, 0, 0x18000
	s_add_i32 s70, 0, 0x1c000
	v_add_u32_e32 v158, s19, v145
	v_add_u32_e32 v169, s70, v145
	ds_read_b128 v[140:143], v158
	ds_read_b128 v[150:153], v158 offset:1024
	ds_read_b128 v[154:157], v158 offset:2048
	ds_read_b128 v[158:161], v158 offset:3072
	ds_read_b128 v[162:165], v169
	ds_read_b128 v[170:173], v169 offset:1024
	ds_read_b128 v[174:177], v169 offset:2048
	ds_read_b128 v[178:181], v169 offset:3072
	s_add_u32 s40, s40, 0x80000
	s_addc_u32 s41, s41, 0
	s_mov_b32 m0, s43
	v_lshl_add_u64 v[220:221], s[40:41], 0, v[128:129]
	ds_read_b128 v[182:185], v149 offset:32768
	ds_read_b128 v[186:189], v149 offset:33792
	ds_read_b128 v[190:193], v149 offset:34816
	ds_read_b128 v[194:197], v149 offset:35840
	ds_read_b128 v[198:201], v149 offset:36864
	ds_read_b128 v[202:205], v149 offset:37888
	ds_read_b128 v[206:209], v149 offset:38912
	ds_read_b128 v[210:213], v149 offset:39936
	global_load_lds_dwordx4 v[220:221], off
	v_lshl_add_u64 v[220:221], s[40:41], 0, v[132:133]
	s_mov_b32 m0, s44
	s_nop 0
	global_load_lds_dwordx4 v[220:221], off
	s_waitcnt vmcnt(8)
	s_waitcnt lgkmcnt(0)
	s_setprio 1
	s_barrier
	v_mfma_f32_16x16x32_bf16 v[124:127], v[140:143], v[182:185], v[124:127]
	v_mfma_f32_16x16x32_bf16 v[120:123], v[154:157], v[182:185], v[120:123]
	v_mfma_f32_16x16x32_bf16 v[108:111], v[140:143], v[190:193], v[108:111]
	v_mfma_f32_16x16x32_bf16 v[104:107], v[154:157], v[190:193], v[104:107]
	v_mfma_f32_16x16x32_bf16 v[92:95], v[140:143], v[198:201], v[92:95]
	v_mfma_f32_16x16x32_bf16 v[88:91], v[154:157], v[198:201], v[88:91]
	v_mfma_f32_16x16x32_bf16 v[76:79], v[140:143], v[206:209], v[76:79]
	v_mfma_f32_16x16x32_bf16 v[72:75], v[154:157], v[206:209], v[72:75]
	v_mfma_f32_16x16x32_bf16 v[124:127], v[150:153], v[186:189], v[124:127]
	v_mfma_f32_16x16x32_bf16 v[120:123], v[158:161], v[186:189], v[120:123]
	v_mfma_f32_16x16x32_bf16 v[108:111], v[150:153], v[194:197], v[108:111]
	v_mfma_f32_16x16x32_bf16 v[104:107], v[158:161], v[194:197], v[104:107]
	v_mfma_f32_16x16x32_bf16 v[92:95], v[150:153], v[202:205], v[92:95]
	v_mfma_f32_16x16x32_bf16 v[88:91], v[158:161], v[202:205], v[88:91]
	v_mfma_f32_16x16x32_bf16 v[76:79], v[150:153], v[210:213], v[76:79]
	v_mfma_f32_16x16x32_bf16 v[72:75], v[158:161], v[210:213], v[72:75]
	v_mfma_f32_16x16x32_bf16 v[116:119], v[162:165], v[182:185], v[116:119]
	v_mfma_f32_16x16x32_bf16 v[112:115], v[174:177], v[182:185], v[112:115]
	v_mfma_f32_16x16x32_bf16 v[100:103], v[162:165], v[190:193], v[100:103]
	v_mfma_f32_16x16x32_bf16 v[96:99], v[174:177], v[190:193], v[96:99]
	v_mfma_f32_16x16x32_bf16 v[84:87], v[162:165], v[198:201], v[84:87]
	v_mfma_f32_16x16x32_bf16 v[80:83], v[174:177], v[198:201], v[80:83]
	v_mfma_f32_16x16x32_bf16 v[68:71], v[162:165], v[206:209], v[68:71]
	v_mfma_f32_16x16x32_bf16 v[64:67], v[174:177], v[206:209], v[64:67]
	v_mfma_f32_16x16x32_bf16 v[116:119], v[170:173], v[186:189], v[116:119]
	v_mfma_f32_16x16x32_bf16 v[112:115], v[178:181], v[186:189], v[112:115]
	v_mfma_f32_16x16x32_bf16 v[100:103], v[170:173], v[194:197], v[100:103]
	v_mfma_f32_16x16x32_bf16 v[96:99], v[178:181], v[194:197], v[96:99]
	v_mfma_f32_16x16x32_bf16 v[84:87], v[170:173], v[202:205], v[84:87]
	v_mfma_f32_16x16x32_bf16 v[80:83], v[178:181], v[202:205], v[80:83]
	v_mfma_f32_16x16x32_bf16 v[68:71], v[170:173], v[210:213], v[68:71]
	v_mfma_f32_16x16x32_bf16 v[64:67], v[178:181], v[210:213], v[64:67]
	s_setprio 0
	s_barrier
; #define PG8_STAGE(bufoff, gbase, voff) do { _Pragma("unroll") for (int _i = 0; _i < 2; ++_i) \
;         __builtin_amdgcn_global_load_lds((const unsigned*)((const char*)(gbase) + (voff)[_i]), (LAS unsigned*)(lds + (bufoff) + ldsw + _i * 8192), 16, 0, 0); } while (0)
; #define PG8_LDA(dst, b, h) do { _Pragma("unroll") for (int m = 0; m < 4; ++m) _Pragma("unroll") for (int k = 0; k < 2; ++k) dst[m][k] = *(const LAS bf16x8*)(lds + PG8_SA(b, h) + aoff + m * 2048 + k * 1024); } while (0)
; #define PG8_MMA(ai, bj, At, Bt) do { __builtin_amdgcn_s_setprio(1); _Pragma("unroll") for (int m = 0; m < 4; ++m) _Pragma("unroll") for (int n = 0; n < 2; ++n) _Pragma("unroll") for (int k = 0; k < 2; ++k) \
;         acc[ai][bj][m][n] = __builtin_amdgcn_mfma_f32_16x16x32_bf16(Bt[n][k], At[m][k], acc[ai][bj][m][n], 0, 0, 0); __builtin_amdgcn_s_setprio(0); } while (0)
; #define PG8_WAIT_V(n) asm volatile("s_waitcnt vmcnt(" #n ")" ::: "memory")
; #define PG8_WAIT_L(n) asm volatile("s_waitcnt lgkmcnt(" #n ")" ::: "memory")
; #define PG8_BAR __builtin_amdgcn_s_barrier()
; #define PG8_SCHED __builtin_amdgcn_sched_barrier(0)
; template <class Epi, class Sched>
; __device__ __forceinline__ void gemm_phase(LAS unsigned char* lds, const int K, const Sched& S, const Epi& E) {
;     ...
;             PG8_LDA(At, 1, 1); PG8_STAGE(PG8_SB(1, 0), b3, voffB); PG8_STAGE(PG8_SB(1, 1), b3 + hstep, voffB); PG8_STAGE(PG8_SA(1, 0), a3, voffA);
;             PG8_WAIT_V(8); PG8_WAIT_L(0); PG8_BAR; PG8_MMA(1, 0, At, B0); PG8_MMA(1, 1, At, B1); PG8_BAR; PG8_SCHED;
;         }
;         if (wr == 0) PG8_BAR;
	s_add_i32 s19, s19, s36
	v_lshl_add_u64 v[166:167], v[166:167], 0, s[10:11]
	s_mov_b32 m0, s19
	ds_read_b128 v[182:185], v149 offset:49152
	ds_read_b128 v[186:189], v149 offset:50176
	ds_read_b128 v[190:193], v149 offset:51200
	ds_read_b128 v[194:197], v149 offset:52224
	ds_read_b128 v[198:201], v149 offset:53248
	ds_read_b128 v[202:205], v149 offset:54272
	ds_read_b128 v[206:209], v149 offset:55296
	ds_read_b128 v[210:213], v149 offset:56320
	global_load_lds_dwordx4 v[166:167], off
	s_add_i32 m0, s19, 0x2000
	s_add_u32 s38, s38, 0x80080
	v_lshl_add_u64 v[166:167], v[214:215], 0, s[10:11]
	s_addc_u32 s39, s39, 0
	s_add_i32 s19, s70, s36
	global_load_lds_dwordx4 v[166:167], off
	v_lshl_add_u64 v[166:167], s[38:39], 0, v[130:131]
	s_mov_b32 m0, s19
	s_nop 0
	global_load_lds_dwordx4 v[166:167], off
	v_lshl_add_u64 v[166:167], s[38:39], 0, v[134:135]
	s_add_i32 m0, s19, 0x2000
	s_nop 0
	global_load_lds_dwordx4 v[166:167], off
	v_lshl_add_u64 v[166:167], v[216:217], 0, s[10:11]
	s_mov_b32 m0, s46
	s_nop 0
	global_load_lds_dwordx4 v[166:167], off
	v_lshl_add_u64 v[166:167], v[218:219], 0, s[10:11]
	s_mov_b32 m0, s47
	s_nop 0
	global_load_lds_dwordx4 v[166:167], off
	s_waitcnt vmcnt(8)
	s_waitcnt lgkmcnt(0)
	s_setprio 1
	s_barrier
	v_mfma_f32_16x16x32_bf16 v[60:63], v[140:143], v[182:185], v[60:63]
	v_mfma_f32_16x16x32_bf16 v[56:59], v[154:157], v[182:185], v[56:59]
	v_mfma_f32_16x16x32_bf16 v[44:47], v[140:143], v[190:193], v[44:47]
	v_mfma_f32_16x16x32_bf16 v[40:43], v[154:157], v[190:193], v[40:43]
	v_mfma_f32_16x16x32_bf16 v[28:31], v[140:143], v[198:201], v[28:31]
	v_mfma_f32_16x16x32_bf16 v[24:27], v[154:157], v[198:201], v[24:27]
	v_mfma_f32_16x16x32_bf16 v[12:15], v[140:143], v[206:209], v[12:15]
	v_mfma_f32_16x16x32_bf16 v[8:11], v[154:157], v[206:209], v[8:11]
	v_mfma_f32_16x16x32_bf16 v[60:63], v[150:153], v[186:189], v[60:63]
	v_mfma_f32_16x16x32_bf16 v[56:59], v[158:161], v[186:189], v[56:59]
	v_mfma_f32_16x16x32_bf16 v[44:47], v[150:153], v[194:197], v[44:47]
	v_mfma_f32_16x16x32_bf16 v[40:43], v[158:161], v[194:197], v[40:43]
	v_mfma_f32_16x16x32_bf16 v[28:31], v[150:153], v[202:205], v[28:31]
	v_mfma_f32_16x16x32_bf16 v[24:27], v[158:161], v[202:205], v[24:27]
	v_mfma_f32_16x16x32_bf16 v[12:15], v[150:153], v[210:213], v[12:15]
	v_mfma_f32_16x16x32_bf16 v[8:11], v[158:161], v[210:213], v[8:11]
	v_mfma_f32_16x16x32_bf16 v[52:55], v[162:165], v[182:185], v[52:55]
	v_mfma_f32_16x16x32_bf16 v[48:51], v[174:177], v[182:185], v[48:51]
	v_mfma_f32_16x16x32_bf16 v[36:39], v[162:165], v[190:193], v[36:39]
	v_mfma_f32_16x16x32_bf16 v[32:35], v[174:177], v[190:193], v[32:35]
	v_mfma_f32_16x16x32_bf16 v[20:23], v[162:165], v[198:201], v[20:23]
	v_mfma_f32_16x16x32_bf16 v[16:19], v[174:177], v[198:201], v[16:19]
	v_mfma_f32_16x16x32_bf16 v[4:7], v[162:165], v[206:209], v[4:7]
	v_mfma_f32_16x16x32_bf16 v[0:3], v[174:177], v[206:209], v[0:3]
	v_mfma_f32_16x16x32_bf16 v[52:55], v[170:173], v[186:189], v[52:55]
	v_mfma_f32_16x16x32_bf16 v[48:51], v[178:181], v[186:189], v[48:51]
	v_mfma_f32_16x16x32_bf16 v[36:39], v[170:173], v[194:197], v[36:39]
	v_mfma_f32_16x16x32_bf16 v[32:35], v[178:181], v[194:197], v[32:35]
	v_mfma_f32_16x16x32_bf16 v[20:23], v[170:173], v[202:205], v[20:23]
	v_mfma_f32_16x16x32_bf16 v[16:19], v[178:181], v[202:205], v[16:19]
	v_mfma_f32_16x16x32_bf16 v[4:7], v[170:173], v[210:213], v[4:7]
	v_mfma_f32_16x16x32_bf16 v[0:3], v[178:181], v[210:213], v[0:3]
	s_setprio 0
	s_barrier
	s_add_i32 s17, s17, 2
	s_add_u32 s34, s34, 0x100
	s_addc_u32 s35, s35, 0
	s_add_u32 s8, s8, 0x100
	s_addc_u32 s9, s9, 0
	s_cmp_gt_u32 s17, 29
	s_cbranch_scc0 .LBB0_485
	s_and_b64 vcc, exec, s[14:15]
	s_cbranch_vccz .LBB0_488
	s_barrier

; #define PG8_STAGE(bufoff, gbase, voff) do { _Pragma("unroll") for (int _i = 0; _i < 2; ++_i) \
;         __builtin_amdgcn_global_load_lds((const unsigned*)((const char*)(gbase) + (voff)[_i]), (LAS unsigned*)(lds + (bufoff) + ldsw + _i * 8192), 16, 0, 0); } while (0)
; #define PG8_LDA(dst, b, h) do { _Pragma("unroll") for (int m = 0; m < 4; ++m) _Pragma("unroll") for (int k = 0; k < 2; ++k) dst[m][k] = *(const LAS bf16x8*)(lds + PG8_SA(b, h) + aoff + m * 2048 + k * 1024); } while (0)
; #define PG8_LDB(dst, b, h) do { _Pragma("unroll") for (int n = 0; n < 2; ++n) _Pragma("unroll") for (int k = 0; k < 2; ++k) dst[n][k] = *(const LAS bf16x8*)(lds + PG8_SB(b, h) + boff + n * 2048 + k * 1024); } while (0)
; #define PG8_MMA(ai, bj, At, Bt) do { __builtin_amdgcn_s_setprio(1); _Pragma("unroll") for (int m = 0; m < 4; ++m) _Pragma("unroll") for (int n = 0; n < 2; ++n) _Pragma("unroll") for (int k = 0; k < 2; ++k) \
;         acc[ai][bj][m][n] = __builtin_amdgcn_mfma_f32_16x16x32_bf16(Bt[n][k], At[m][k], acc[ai][bj][m][n], 0, 0, 0); __builtin_amdgcn_s_setprio(0); } while (0)
; #define PG8_WAIT_V(n) asm volatile("s_waitcnt vmcnt(" #n ")" ::: "memory")
; #define PG8_WAIT_L(n) asm volatile("s_waitcnt lgkmcnt(" #n ")" ::: "memory")
; #define PG8_BAR __builtin_amdgcn_s_barrier()
; #define PG8_SCHED __builtin_amdgcn_sched_barrier(0)
; template <class Epi, class Sched>
; __device__ __forceinline__ void gemm_phase(LAS unsigned char* lds, const int K, const Sched& S, const Epi& E) {
;     ...
;             const char* a1 = cA + (size_t)(t + 1) * kstep;
;             const char* a2 = last ? nA : cA + (size_t)(t + 2) * kstep; const char* b2 = last ? nB : cB + (size_t)(t + 2) * kstep;
;             const char* a3 = a2 + kstep; const char* b3 = b2 + kstep;
;             PG8_LDB(B0, 0, 0); PG8_LDB(B1, 0, 1); PG8_SCHED; PG8_LDA(At, 0, 0); PG8_STAGE(PG8_SA(1, 1), a1 + hstep, voffA);
;             PG8_WAIT_V(8); PG8_WAIT_L(0); PG8_BAR; PG8_MMA(0, 0, At, B0); PG8_MMA(0, 1, At, B1); PG8_BAR; PG8_SCHED;
;             PG8_LDA(At, 0, 1); PG8_STAGE(PG8_SB(0, 0), b2, voffB); PG8_STAGE(PG8_SB(0, 1), b2 + hstep, voffB); PG8_STAGE(PG8_SA(0, 0), a2, voffA);
;             PG8_WAIT_V(8); PG8_WAIT_L(0); PG8_BAR; PG8_MMA(1, 0, At, B0); PG8_MMA(1, 1, At, B1); PG8_BAR; PG8_SCHED;
.LBB0_565:
	ds_read_b128 v[140:143], v147
	ds_read_b128 v[152:155], v147 offset:1024
	ds_read_b128 v[156:159], v147 offset:2048
	ds_read_b128 v[160:163], v147 offset:3072
	ds_read_b128 v[164:167], v148
	ds_read_b128 v[170:173], v148 offset:1024
	ds_read_b128 v[174:177], v148 offset:2048
	ds_read_b128 v[178:181], v148 offset:3072
	s_add_u32 s24, s22, 0xffea0080
	s_addc_u32 s25, s23, -1
	s_cmpk_eq_i32 s71, 0x54
	s_cselect_b32 s31, s17, s25
	s_cselect_b32 s30, s16, s24
	s_cselect_b32 s25, s19, s9
	s_cselect_b32 s24, s18, s8
	s_mov_b32 m0, s46
	v_lshl_add_u64 v[214:215], s[22:23], 0, v[136:137]
	ds_read_b128 v[182:185], v149
	ds_read_b128 v[186:189], v149 offset:1024
	ds_read_b128 v[190:193], v149 offset:2048
	ds_read_b128 v[194:197], v149 offset:3072
	ds_read_b128 v[198:201], v149 offset:4096
	ds_read_b128 v[202:205], v149 offset:5120
	ds_read_b128 v[206:209], v149 offset:6144
	ds_read_b128 v[210:213], v149 offset:7168
	global_load_lds_dwordx4 v[214:215], off
	v_lshl_add_u64 v[214:215], s[22:23], 0, v[138:139]
	s_mov_b32 m0, s47
	s_nop 0
	global_load_lds_dwordx4 v[214:215], off
	s_waitcnt vmcnt(8)
	s_waitcnt lgkmcnt(0)
	s_setprio 1
	s_barrier
	v_mfma_f32_16x16x32_bf16 v[124:127], v[140:143], v[182:185], v[124:127]
	v_mfma_f32_16x16x32_bf16 v[120:123], v[156:159], v[182:185], v[120:123]
	v_mfma_f32_16x16x32_bf16 v[108:111], v[140:143], v[190:193], v[108:111]
	v_mfma_f32_16x16x32_bf16 v[104:107], v[156:159], v[190:193], v[104:107]
	v_mfma_f32_16x16x32_bf16 v[92:95], v[140:143], v[198:201], v[92:95]
	v_mfma_f32_16x16x32_bf16 v[88:91], v[156:159], v[198:201], v[88:91]
	v_mfma_f32_16x16x32_bf16 v[76:79], v[140:143], v[206:209], v[76:79]
	v_mfma_f32_16x16x32_bf16 v[72:75], v[156:159], v[206:209], v[72:75]
	v_mfma_f32_16x16x32_bf16 v[124:127], v[152:155], v[186:189], v[124:127]
	v_mfma_f32_16x16x32_bf16 v[120:123], v[160:163], v[186:189], v[120:123]
	v_mfma_f32_16x16x32_bf16 v[108:111], v[152:155], v[194:197], v[108:111]
	v_mfma_f32_16x16x32_bf16 v[104:107], v[160:163], v[194:197], v[104:107]
	v_mfma_f32_16x16x32_bf16 v[92:95], v[152:155], v[202:205], v[92:95]
	v_mfma_f32_16x16x32_bf16 v[88:91], v[160:163], v[202:205], v[88:91]
	v_mfma_f32_16x16x32_bf16 v[76:79], v[152:155], v[210:213], v[76:79]
	v_mfma_f32_16x16x32_bf16 v[72:75], v[160:163], v[210:213], v[72:75]
	v_mfma_f32_16x16x32_bf16 v[116:119], v[164:167], v[182:185], v[116:119]
	v_mfma_f32_16x16x32_bf16 v[112:115], v[174:177], v[182:185], v[112:115]
	v_mfma_f32_16x16x32_bf16 v[100:103], v[164:167], v[190:193], v[100:103]
	v_mfma_f32_16x16x32_bf16 v[96:99], v[174:177], v[190:193], v[96:99]
	v_mfma_f32_16x16x32_bf16 v[84:87], v[164:167], v[198:201], v[84:87]
	v_mfma_f32_16x16x32_bf16 v[80:83], v[174:177], v[198:201], v[80:83]
	v_mfma_f32_16x16x32_bf16 v[68:71], v[164:167], v[206:209], v[68:71]
	v_mfma_f32_16x16x32_bf16 v[64:67], v[174:177], v[206:209], v[64:67]
	v_mfma_f32_16x16x32_bf16 v[116:119], v[170:173], v[186:189], v[116:119]
	v_mfma_f32_16x16x32_bf16 v[112:115], v[178:181], v[186:189], v[112:115]
	v_mfma_f32_16x16x32_bf16 v[100:103], v[170:173], v[194:197], v[100:103]
	v_mfma_f32_16x16x32_bf16 v[96:99], v[178:181], v[194:197], v[96:99]
	v_mfma_f32_16x16x32_bf16 v[84:87], v[170:173], v[202:205], v[84:87]
	v_mfma_f32_16x16x32_bf16 v[80:83], v[178:181], v[202:205], v[80:83]
	v_mfma_f32_16x16x32_bf16 v[68:71], v[170:173], v[210:213], v[68:71]
	v_mfma_f32_16x16x32_bf16 v[64:67], v[178:181], v[210:213], v[64:67]
	s_setprio 0
	s_barrier
	s_mov_b32 m0, s48
	v_lshl_add_u64 v[214:215], s[24:25], 0, v[130:131]
	s_add_u32 s72, s24, 0x160000
	ds_read_b128 v[182:185], v149 offset:16384
	ds_read_b128 v[186:189], v149 offset:17408
	ds_read_b128 v[190:193], v149 offset:18432
	ds_read_b128 v[194:197], v149 offset:19456
	ds_read_b128 v[198:201], v149 offset:20480
	ds_read_b128 v[202:205], v149 offset:21504
	ds_read_b128 v[206:209], v149 offset:22528
	ds_read_b128 v[210:213], v149 offset:23552
	global_load_lds_dwordx4 v[214:215], off
	v_lshl_add_u64 v[216:217], s[24:25], 0, v[134:135]
	s_mov_b32 m0, s49
	s_addc_u32 s73, s25, 0
	global_load_lds_dwordx4 v[216:217], off
	v_lshl_add_u64 v[218:219], s[72:73], 0, v[130:131]
	s_mov_b32 m0, s50
	v_lshl_add_u64 v[220:221], s[30:31], 0, v[132:133]
	global_load_lds_dwordx4 v[218:219], off
	v_lshl_add_u64 v[218:219], s[72:73], 0, v[134:135]
	s_add_i32 m0, s50, 0x2000
	s_nop 0
	global_load_lds_dwordx4 v[218:219], off
	v_lshl_add_u64 v[218:219], s[30:31], 0, v[128:129]
	s_mov_b32 m0, s37
	s_nop 0
	global_load_lds_dwordx4 v[218:219], off
	s_mov_b32 m0, s38
	s_nop 0
	global_load_lds_dwordx4 v[220:221], off
	s_waitcnt vmcnt(8)
	s_waitcnt lgkmcnt(0)
	s_setprio 1
	s_barrier
; #define PG8_STAGE(bufoff, gbase, voff) do { _Pragma("unroll") for (int _i = 0; _i < 2; ++_i) \
;         __builtin_amdgcn_global_load_lds((const unsigned*)((const char*)(gbase) + (voff)[_i]), (LAS unsigned*)(lds + (bufoff) + ldsw + _i * 8192), 16, 0, 0); } while (0)
; #define PG8_LDA(dst, b, h) do { _Pragma("unroll") for (int m = 0; m < 4; ++m) _Pragma("unroll") for (int k = 0; k < 2; ++k) dst[m][k] = *(const LAS bf16x8*)(lds + PG8_SA(b, h) + aoff + m * 2048 + k * 1024); } while (0)
; #define PG8_LDB(dst, b, h) do { _Pragma("unroll") for (int n = 0; n < 2; ++n) _Pragma("unroll") for (int k = 0; k < 2; ++k) dst[n][k] = *(const LAS bf16x8*)(lds + PG8_SB(b, h) + boff + n * 2048 + k * 1024); } while (0)
; #define PG8_MMA(ai, bj, At, Bt) do { __builtin_amdgcn_s_setprio(1); _Pragma("unroll") for (int m = 0; m < 4; ++m) _Pragma("unroll") for (int n = 0; n < 2; ++n) _Pragma("unroll") for (int k = 0; k < 2; ++k) \
;         acc[ai][bj][m][n] = __builtin_amdgcn_mfma_f32_16x16x32_bf16(Bt[n][k], At[m][k], acc[ai][bj][m][n], 0, 0, 0); __builtin_amdgcn_s_setprio(0); } while (0)
; #define PG8_WAIT_V(n) asm volatile("s_waitcnt vmcnt(" #n ")" ::: "memory")
; #define PG8_WAIT_L(n) asm volatile("s_waitcnt lgkmcnt(" #n ")" ::: "memory")
; #define PG8_BAR __builtin_amdgcn_s_barrier()
; #define PG8_SCHED __builtin_amdgcn_sched_barrier(0)
; template <class Epi, class Sched>
; __device__ __forceinline__ void gemm_phase(LAS unsigned char* lds, const int K, const Sched& S, const Epi& E) {
;     ...
;             PG8_WAIT_V(8); PG8_WAIT_L(0); PG8_BAR; PG8_MMA(1, 0, At, B0); PG8_MMA(1, 1, At, B1); PG8_BAR; PG8_SCHED;
;             PG8_LDB(B0, 1, 0); PG8_LDB(B1, 1, 1); PG8_SCHED; PG8_LDA(At, 1, 0); PG8_STAGE(PG8_SA(0, 1), a2 + hstep, voffA);
;             PG8_WAIT_V(8); PG8_WAIT_L(0); PG8_BAR; PG8_MMA(0, 0, At, B0); PG8_MMA(0, 1, At, B1); PG8_BAR; PG8_SCHED;
	v_mfma_f32_16x16x32_bf16 v[60:63], v[140:143], v[182:185], v[60:63]
	v_mfma_f32_16x16x32_bf16 v[56:59], v[156:159], v[182:185], v[56:59]
	v_mfma_f32_16x16x32_bf16 v[44:47], v[140:143], v[190:193], v[44:47]
	v_mfma_f32_16x16x32_bf16 v[40:43], v[156:159], v[190:193], v[40:43]
	v_mfma_f32_16x16x32_bf16 v[28:31], v[140:143], v[198:201], v[28:31]
	v_mfma_f32_16x16x32_bf16 v[24:27], v[156:159], v[198:201], v[24:27]
	v_mfma_f32_16x16x32_bf16 v[12:15], v[140:143], v[206:209], v[12:15]
	v_mfma_f32_16x16x32_bf16 v[8:11], v[156:159], v[206:209], v[8:11]
	v_mfma_f32_16x16x32_bf16 v[60:63], v[152:155], v[186:189], v[60:63]
	v_mfma_f32_16x16x32_bf16 v[56:59], v[160:163], v[186:189], v[56:59]
	v_mfma_f32_16x16x32_bf16 v[44:47], v[152:155], v[194:197], v[44:47]
	v_mfma_f32_16x16x32_bf16 v[40:43], v[160:163], v[194:197], v[40:43]
	v_mfma_f32_16x16x32_bf16 v[28:31], v[152:155], v[202:205], v[28:31]
	v_mfma_f32_16x16x32_bf16 v[24:27], v[160:163], v[202:205], v[24:27]
	v_mfma_f32_16x16x32_bf16 v[12:15], v[152:155], v[210:213], v[12:15]
	v_mfma_f32_16x16x32_bf16 v[8:11], v[160:163], v[210:213], v[8:11]
	v_mfma_f32_16x16x32_bf16 v[52:55], v[164:167], v[182:185], v[52:55]
	v_mfma_f32_16x16x32_bf16 v[48:51], v[174:177], v[182:185], v[48:51]
	v_mfma_f32_16x16x32_bf16 v[36:39], v[164:167], v[190:193], v[36:39]
	v_mfma_f32_16x16x32_bf16 v[32:35], v[174:177], v[190:193], v[32:35]
	v_mfma_f32_16x16x32_bf16 v[20:23], v[164:167], v[198:201], v[20:23]
	v_mfma_f32_16x16x32_bf16 v[16:19], v[174:177], v[198:201], v[16:19]
	v_mfma_f32_16x16x32_bf16 v[4:7], v[164:167], v[206:209], v[4:7]
	v_mfma_f32_16x16x32_bf16 v[0:3], v[174:177], v[206:209], v[0:3]
	v_mfma_f32_16x16x32_bf16 v[52:55], v[170:173], v[186:189], v[52:55]
	v_mfma_f32_16x16x32_bf16 v[48:51], v[178:181], v[186:189], v[48:51]
	v_mfma_f32_16x16x32_bf16 v[36:39], v[170:173], v[194:197], v[36:39]
	v_mfma_f32_16x16x32_bf16 v[32:35], v[178:181], v[194:197], v[32:35]
	v_mfma_f32_16x16x32_bf16 v[20:23], v[170:173], v[202:205], v[20:23]
	v_mfma_f32_16x16x32_bf16 v[16:19], v[178:181], v[202:205], v[16:19]
	v_mfma_f32_16x16x32_bf16 v[4:7], v[170:173], v[210:213], v[4:7]
	v_mfma_f32_16x16x32_bf16 v[0:3], v[178:181], v[210:213], v[0:3]
	s_setprio 0
	s_barrier
	s_add_i32 s72, 0, 0x18000
	v_add_u32_e32 v151, s72, v146
	s_add_i32 s73, 0, 0x1c000
	ds_read_b128 v[140:143], v151
	ds_read_b128 v[152:155], v151 offset:1024
	ds_read_b128 v[156:159], v151 offset:2048
	ds_read_b128 v[160:163], v151 offset:3072
	v_add_u32_e32 v151, s73, v146
	ds_read_b128 v[164:167], v151
	ds_read_b128 v[170:173], v151 offset:1024
	ds_read_b128 v[174:177], v151 offset:2048
	ds_read_b128 v[178:181], v151 offset:3072
	s_add_u32 s30, s30, 0x160000
	s_addc_u32 s31, s31, 0
	s_mov_b32 m0, s39
	v_lshl_add_u64 v[224:225], s[30:31], 0, v[128:129]
	ds_read_b128 v[182:185], v149 offset:32768
	ds_read_b128 v[186:189], v149 offset:33792
	ds_read_b128 v[190:193], v149 offset:34816
	ds_read_b128 v[194:197], v149 offset:35840
	ds_read_b128 v[198:201], v149 offset:36864
	ds_read_b128 v[202:205], v149 offset:37888
	ds_read_b128 v[206:209], v149 offset:38912
	ds_read_b128 v[210:213], v149 offset:39936
	global_load_lds_dwordx4 v[224:225], off
	v_lshl_add_u64 v[224:225], s[30:31], 0, v[132:133]
	s_mov_b32 m0, s40
	s_nop 0
	global_load_lds_dwordx4 v[224:225], off
	s_waitcnt vmcnt(8)
	s_waitcnt lgkmcnt(0)
	s_setprio 1
	s_barrier
	v_mfma_f32_16x16x32_bf16 v[124:127], v[140:143], v[182:185], v[124:127]
	v_mfma_f32_16x16x32_bf16 v[120:123], v[156:159], v[182:185], v[120:123]
	v_mfma_f32_16x16x32_bf16 v[108:111], v[140:143], v[190:193], v[108:111]
	v_mfma_f32_16x16x32_bf16 v[104:107], v[156:159], v[190:193], v[104:107]
	v_mfma_f32_16x16x32_bf16 v[92:95], v[140:143], v[198:201], v[92:95]
	v_mfma_f32_16x16x32_bf16 v[88:91], v[156:159], v[198:201], v[88:91]
	v_mfma_f32_16x16x32_bf16 v[76:79], v[140:143], v[206:209], v[76:79]
	v_mfma_f32_16x16x32_bf16 v[72:75], v[156:159], v[206:209], v[72:75]
	v_mfma_f32_16x16x32_bf16 v[124:127], v[152:155], v[186:189], v[124:127]
	v_mfma_f32_16x16x32_bf16 v[120:123], v[160:163], v[186:189], v[120:123]
	v_mfma_f32_16x16x32_bf16 v[108:111], v[152:155], v[194:197], v[108:111]
	v_mfma_f32_16x16x32_bf16 v[104:107], v[160:163], v[194:197], v[104:107]
	v_mfma_f32_16x16x32_bf16 v[92:95], v[152:155], v[202:205], v[92:95]
	v_mfma_f32_16x16x32_bf16 v[88:91], v[160:163], v[202:205], v[88:91]
	v_mfma_f32_16x16x32_bf16 v[76:79], v[152:155], v[210:213], v[76:79]
	v_mfma_f32_16x16x32_bf16 v[72:75], v[160:163], v[210:213], v[72:75]
	v_mfma_f32_16x16x32_bf16 v[116:119], v[164:167], v[182:185], v[116:119]
	v_mfma_f32_16x16x32_bf16 v[112:115], v[174:177], v[182:185], v[112:115]
	v_mfma_f32_16x16x32_bf16 v[100:103], v[164:167], v[190:193], v[100:103]
	v_mfma_f32_16x16x32_bf16 v[96:99], v[174:177], v[190:193], v[96:99]
	v_mfma_f32_16x16x32_bf16 v[84:87], v[164:167], v[198:201], v[84:87]
	v_mfma_f32_16x16x32_bf16 v[80:83], v[174:177], v[198:201], v[80:83]
	v_mfma_f32_16x16x32_bf16 v[68:71], v[164:167], v[206:209], v[68:71]
	v_mfma_f32_16x16x32_bf16 v[64:67], v[174:177], v[206:209], v[64:67]
	v_mfma_f32_16x16x32_bf16 v[116:119], v[170:173], v[186:189], v[116:119]
	v_mfma_f32_16x16x32_bf16 v[112:115], v[178:181], v[186:189], v[112:115]
	v_mfma_f32_16x16x32_bf16 v[100:103], v[170:173], v[194:197], v[100:103]
	v_mfma_f32_16x16x32_bf16 v[96:99], v[178:181], v[194:197], v[96:99]
	v_mfma_f32_16x16x32_bf16 v[84:87], v[170:173], v[202:205], v[84:87]
	v_mfma_f32_16x16x32_bf16 v[80:83], v[178:181], v[202:205], v[80:83]
	v_mfma_f32_16x16x32_bf16 v[68:71], v[170:173], v[210:213], v[68:71]
	v_mfma_f32_16x16x32_bf16 v[64:67], v[178:181], v[210:213], v[64:67]
	s_setprio 0
	s_barrier
; #define PG8_STAGE(bufoff, gbase, voff) do { _Pragma("unroll") for (int _i = 0; _i < 2; ++_i) \
;         __builtin_amdgcn_global_load_lds((const unsigned*)((const char*)(gbase) + (voff)[_i]), (LAS unsigned*)(lds + (bufoff) + ldsw + _i * 8192), 16, 0, 0); } while (0)
; #define PG8_LDA(dst, b, h) do { _Pragma("unroll") for (int m = 0; m < 4; ++m) _Pragma("unroll") for (int k = 0; k < 2; ++k) dst[m][k] = *(const LAS bf16x8*)(lds + PG8_SA(b, h) + aoff + m * 2048 + k * 1024); } while (0)
; #define PG8_MMA(ai, bj, At, Bt) do { __builtin_amdgcn_s_setprio(1); _Pragma("unroll") for (int m = 0; m < 4; ++m) _Pragma("unroll") for (int n = 0; n < 2; ++n) _Pragma("unroll") for (int k = 0; k < 2; ++k) \
;         acc[ai][bj][m][n] = __builtin_amdgcn_mfma_f32_16x16x32_bf16(Bt[n][k], At[m][k], acc[ai][bj][m][n], 0, 0, 0); __builtin_amdgcn_s_setprio(0); } while (0)
; #define PG8_WAIT_V(n) asm volatile("s_waitcnt vmcnt(" #n ")" ::: "memory")
; #define PG8_WAIT_L(n) asm volatile("s_waitcnt lgkmcnt(" #n ")" ::: "memory")
; #define PG8_BAR __builtin_amdgcn_s_barrier()
; #define PG8_SCHED __builtin_amdgcn_sched_barrier(0)
; template <class Epi, class Sched>
; __device__ __forceinline__ void gemm_phase(LAS unsigned char* lds, const int K, const Sched& S, const Epi& E) {
;     ...
;             PG8_LDA(At, 1, 1); PG8_STAGE(PG8_SB(1, 0), b3, voffB); PG8_STAGE(PG8_SB(1, 1), b3 + hstep, voffB); PG8_STAGE(PG8_SA(1, 0), a3, voffA);
;             PG8_WAIT_V(8); PG8_WAIT_L(0); PG8_BAR; PG8_MMA(1, 0, At, B0); PG8_MMA(1, 1, At, B1); PG8_BAR; PG8_SCHED;
;         }
;         if (wr == 0) PG8_BAR;
	s_add_i32 s30, s72, s36
	v_lshl_add_u64 v[214:215], v[214:215], 0, s[10:11]
	s_mov_b32 m0, s30
	ds_read_b128 v[182:185], v149 offset:49152
	ds_read_b128 v[186:189], v149 offset:50176
	ds_read_b128 v[190:193], v149 offset:51200
	ds_read_b128 v[194:197], v149 offset:52224
	ds_read_b128 v[198:201], v149 offset:53248
	ds_read_b128 v[202:205], v149 offset:54272
	ds_read_b128 v[206:209], v149 offset:55296
	ds_read_b128 v[210:213], v149 offset:56320
	global_load_lds_dwordx4 v[214:215], off
	s_add_i32 m0, s30, 0x2000
	s_add_u32 s24, s24, 0x160080
	v_lshl_add_u64 v[214:215], v[216:217], 0, s[10:11]
	s_addc_u32 s25, s25, 0
	s_add_i32 s30, s73, s36
	global_load_lds_dwordx4 v[214:215], off
	v_lshl_add_u64 v[214:215], s[24:25], 0, v[130:131]
	s_mov_b32 m0, s30
	s_nop 0
	global_load_lds_dwordx4 v[214:215], off
	v_lshl_add_u64 v[214:215], s[24:25], 0, v[134:135]
	s_add_i32 m0, s30, 0x2000
	s_nop 0
	global_load_lds_dwordx4 v[214:215], off
	v_lshl_add_u64 v[214:215], v[218:219], 0, s[10:11]
	s_mov_b32 m0, s44
	s_nop 0
	global_load_lds_dwordx4 v[214:215], off
	v_lshl_add_u64 v[214:215], v[220:221], 0, s[10:11]
	s_mov_b32 m0, s45
	s_nop 0
	global_load_lds_dwordx4 v[214:215], off
	s_waitcnt vmcnt(8)
	s_waitcnt lgkmcnt(0)
	s_setprio 1
	s_barrier
	v_mfma_f32_16x16x32_bf16 v[60:63], v[140:143], v[182:185], v[60:63]
	v_mfma_f32_16x16x32_bf16 v[56:59], v[156:159], v[182:185], v[56:59]
	v_mfma_f32_16x16x32_bf16 v[44:47], v[140:143], v[190:193], v[44:47]
	v_mfma_f32_16x16x32_bf16 v[40:43], v[156:159], v[190:193], v[40:43]
	v_mfma_f32_16x16x32_bf16 v[28:31], v[140:143], v[198:201], v[28:31]
	v_mfma_f32_16x16x32_bf16 v[24:27], v[156:159], v[198:201], v[24:27]
	v_mfma_f32_16x16x32_bf16 v[12:15], v[140:143], v[206:209], v[12:15]
	v_mfma_f32_16x16x32_bf16 v[8:11], v[156:159], v[206:209], v[8:11]
	v_mfma_f32_16x16x32_bf16 v[60:63], v[152:155], v[186:189], v[60:63]
	v_mfma_f32_16x16x32_bf16 v[56:59], v[160:163], v[186:189], v[56:59]
	v_mfma_f32_16x16x32_bf16 v[44:47], v[152:155], v[194:197], v[44:47]
	v_mfma_f32_16x16x32_bf16 v[40:43], v[160:163], v[194:197], v[40:43]
	v_mfma_f32_16x16x32_bf16 v[28:31], v[152:155], v[202:205], v[28:31]
	v_mfma_f32_16x16x32_bf16 v[24:27], v[160:163], v[202:205], v[24:27]
	v_mfma_f32_16x16x32_bf16 v[12:15], v[152:155], v[210:213], v[12:15]
	v_mfma_f32_16x16x32_bf16 v[8:11], v[160:163], v[210:213], v[8:11]
	v_mfma_f32_16x16x32_bf16 v[52:55], v[164:167], v[182:185], v[52:55]
	v_mfma_f32_16x16x32_bf16 v[48:51], v[174:177], v[182:185], v[48:51]
	v_mfma_f32_16x16x32_bf16 v[36:39], v[164:167], v[190:193], v[36:39]
	v_mfma_f32_16x16x32_bf16 v[32:35], v[174:177], v[190:193], v[32:35]
	v_mfma_f32_16x16x32_bf16 v[20:23], v[164:167], v[198:201], v[20:23]
	v_mfma_f32_16x16x32_bf16 v[16:19], v[174:177], v[198:201], v[16:19]
	v_mfma_f32_16x16x32_bf16 v[4:7], v[164:167], v[206:209], v[4:7]
	v_mfma_f32_16x16x32_bf16 v[0:3], v[174:177], v[206:209], v[0:3]
	v_mfma_f32_16x16x32_bf16 v[52:55], v[170:173], v[186:189], v[52:55]
	v_mfma_f32_16x16x32_bf16 v[48:51], v[178:181], v[186:189], v[48:51]
	v_mfma_f32_16x16x32_bf16 v[36:39], v[170:173], v[194:197], v[36:39]
	v_mfma_f32_16x16x32_bf16 v[32:35], v[178:181], v[194:197], v[32:35]
	v_mfma_f32_16x16x32_bf16 v[20:23], v[170:173], v[202:205], v[20:23]
	v_mfma_f32_16x16x32_bf16 v[16:19], v[178:181], v[202:205], v[16:19]
	v_mfma_f32_16x16x32_bf16 v[4:7], v[170:173], v[210:213], v[4:7]
	v_mfma_f32_16x16x32_bf16 v[0:3], v[178:181], v[210:213], v[0:3]
	s_setprio 0
	s_barrier
	s_add_i32 s71, s71, 2
	s_add_u32 s22, s22, 0x100
	s_addc_u32 s23, s23, 0
	s_add_u32 s8, s8, 0x100
	s_addc_u32 s9, s9, 0
	s_cmpk_gt_u32 s71, 0x55
	s_cbranch_scc0 .LBB0_565
	s_and_b64 vcc, exec, s[14:15]
	s_cbranch_vccz .LBB0_568
	s_barrier

; #define PG8_STAGE(bufoff, gbase, voff) do { _Pragma("unroll") for (int _i = 0; _i < 2; ++_i) \
;         __builtin_amdgcn_global_load_lds((const unsigned*)((const char*)(gbase) + (voff)[_i]), (LAS unsigned*)(lds + (bufoff) + ldsw + _i * 8192), 16, 0, 0); } while (0)
; #define PG8_LDA(dst, b, h) do { _Pragma("unroll") for (int m = 0; m < 4; ++m) _Pragma("unroll") for (int k = 0; k < 2; ++k) dst[m][k] = *(const LAS bf16x8*)(lds + PG8_SA(b, h) + aoff + m * 2048 + k * 1024); } while (0)
; #define PG8_LDB(dst, b, h) do { _Pragma("unroll") for (int n = 0; n < 2; ++n) _Pragma("unroll") for (int k = 0; k < 2; ++k) dst[n][k] = *(const LAS bf16x8*)(lds + PG8_SB(b, h) + boff + n * 2048 + k * 1024); } while (0)
; #define PG8_MMA(ai, bj, At, Bt) do { __builtin_amdgcn_s_setprio(1); _Pragma("unroll") for (int m = 0; m < 4; ++m) _Pragma("unroll") for (int n = 0; n < 2; ++n) _Pragma("unroll") for (int k = 0; k < 2; ++k) \
;         acc[ai][bj][m][n] = __builtin_amdgcn_mfma_f32_16x16x32_bf16(Bt[n][k], At[m][k], acc[ai][bj][m][n], 0, 0, 0); __builtin_amdgcn_s_setprio(0); } while (0)
; #define PG8_WAIT_V(n) asm volatile("s_waitcnt vmcnt(" #n ")" ::: "memory")
; #define PG8_WAIT_L(n) asm volatile("s_waitcnt lgkmcnt(" #n ")" ::: "memory")
; #define PG8_BAR __builtin_amdgcn_s_barrier()
; #define PG8_SCHED __builtin_amdgcn_sched_barrier(0)
; template <class Epi, class Sched>
; __device__ __forceinline__ void gemm_phase(LAS unsigned char* lds, const int K, const Sched& S, const Epi& E) {
;     ...
;             const char* a1 = cA + (size_t)(t + 1) * kstep;
;             const char* a2 = last ? nA : cA + (size_t)(t + 2) * kstep; const char* b2 = last ? nB : cB + (size_t)(t + 2) * kstep;
;             const char* a3 = a2 + kstep; const char* b3 = b2 + kstep;
;             PG8_LDB(B0, 0, 0); PG8_LDB(B1, 0, 1); PG8_SCHED; PG8_LDA(At, 0, 0); PG8_STAGE(PG8_SA(1, 1), a1 + hstep, voffA);
;             PG8_WAIT_V(8); PG8_WAIT_L(0); PG8_BAR; PG8_MMA(0, 0, At, B0); PG8_MMA(0, 1, At, B1); PG8_BAR; PG8_SCHED;
;             PG8_LDA(At, 0, 1); PG8_STAGE(PG8_SB(0, 0), b2, voffB); PG8_STAGE(PG8_SB(0, 1), b2 + hstep, voffB); PG8_STAGE(PG8_SA(0, 0), a2, voffA);
;             PG8_WAIT_V(8); PG8_WAIT_L(0); PG8_BAR; PG8_MMA(1, 0, At, B0); PG8_MMA(1, 1, At, B1); PG8_BAR; PG8_SCHED;
.LBB0_661:
	ds_read_b128 v[0:3], v227
	ds_read_b128 v[4:7], v227 offset:1024
	ds_read_b128 v[8:11], v227 offset:2048
	ds_read_b128 v[12:15], v227 offset:3072
	ds_read_b128 v[16:19], v228
	ds_read_b128 v[20:23], v228 offset:1024
	ds_read_b128 v[152:155], v228 offset:2048
	ds_read_b128 v[156:159], v228 offset:3072
	s_add_u32 s36, s6, 0xfff80080
	s_addc_u32 s37, s7, -1
	s_cmp_eq_u32 s9, 28
	s_cselect_b32 s75, s69, s37
	s_cselect_b32 s74, s68, s36
	s_cselect_b32 s73, s71, s8
	s_cselect_b32 s72, s70, s1
	v_lshl_add_u64 v[210:211], s[6:7], 0, v[180:181]
	s_add_i32 m0, s47, 0xc000
	ds_read_b128 v[160:163], v229
	ds_read_b128 v[164:167], v229 offset:1024
	ds_read_b128 v[186:189], v229 offset:2048
	ds_read_b128 v[190:193], v229 offset:3072
	ds_read_b128 v[194:197], v229 offset:4096
	ds_read_b128 v[198:201], v229 offset:5120
	ds_read_b128 v[202:205], v229 offset:6144
	ds_read_b128 v[206:209], v229 offset:7168
	global_load_lds_dwordx4 v[210:211], off
	v_lshl_add_u64 v[210:211], s[6:7], 0, v[182:183]
	s_add_i32 m0, s47, 0xe000
	s_nop 0
	global_load_lds_dwordx4 v[210:211], off
	s_waitcnt vmcnt(8)
	s_waitcnt lgkmcnt(0)
	s_setprio 1
	s_barrier
	v_mfma_f32_16x16x32_bf16 v[148:151], v[0:3], v[160:163], v[148:151]
	v_mfma_f32_16x16x32_bf16 v[144:147], v[8:11], v[160:163], v[144:147]
	v_mfma_f32_16x16x32_bf16 v[132:135], v[0:3], v[186:189], v[132:135]
	v_mfma_f32_16x16x32_bf16 v[128:131], v[8:11], v[186:189], v[128:131]
	v_mfma_f32_16x16x32_bf16 v[116:119], v[0:3], v[194:197], v[116:119]
	v_mfma_f32_16x16x32_bf16 v[112:115], v[8:11], v[194:197], v[112:115]
	v_mfma_f32_16x16x32_bf16 v[100:103], v[0:3], v[202:205], v[100:103]
	v_mfma_f32_16x16x32_bf16 v[96:99], v[8:11], v[202:205], v[96:99]
	v_mfma_f32_16x16x32_bf16 v[148:151], v[4:7], v[164:167], v[148:151]
	v_mfma_f32_16x16x32_bf16 v[144:147], v[12:15], v[164:167], v[144:147]
	v_mfma_f32_16x16x32_bf16 v[132:135], v[4:7], v[190:193], v[132:135]
	v_mfma_f32_16x16x32_bf16 v[128:131], v[12:15], v[190:193], v[128:131]
	v_mfma_f32_16x16x32_bf16 v[116:119], v[4:7], v[198:201], v[116:119]
	v_mfma_f32_16x16x32_bf16 v[112:115], v[12:15], v[198:201], v[112:115]
	v_mfma_f32_16x16x32_bf16 v[100:103], v[4:7], v[206:209], v[100:103]
	v_mfma_f32_16x16x32_bf16 v[96:99], v[12:15], v[206:209], v[96:99]
	v_mfma_f32_16x16x32_bf16 v[140:143], v[16:19], v[160:163], v[140:143]
	v_mfma_f32_16x16x32_bf16 v[136:139], v[152:155], v[160:163], v[136:139]
	v_mfma_f32_16x16x32_bf16 v[124:127], v[16:19], v[186:189], v[124:127]
	v_mfma_f32_16x16x32_bf16 v[120:123], v[152:155], v[186:189], v[120:123]
	v_mfma_f32_16x16x32_bf16 v[108:111], v[16:19], v[194:197], v[108:111]
	v_mfma_f32_16x16x32_bf16 v[104:107], v[152:155], v[194:197], v[104:107]
	v_mfma_f32_16x16x32_bf16 v[92:95], v[16:19], v[202:205], v[92:95]
	v_mfma_f32_16x16x32_bf16 v[88:91], v[152:155], v[202:205], v[88:91]
	v_mfma_f32_16x16x32_bf16 v[140:143], v[20:23], v[164:167], v[140:143]
	v_mfma_f32_16x16x32_bf16 v[136:139], v[156:159], v[164:167], v[136:139]
	v_mfma_f32_16x16x32_bf16 v[124:127], v[20:23], v[190:193], v[124:127]
	v_mfma_f32_16x16x32_bf16 v[120:123], v[156:159], v[190:193], v[120:123]
	v_mfma_f32_16x16x32_bf16 v[108:111], v[20:23], v[198:201], v[108:111]
	v_mfma_f32_16x16x32_bf16 v[104:107], v[156:159], v[198:201], v[104:107]
	v_mfma_f32_16x16x32_bf16 v[92:95], v[20:23], v[206:209], v[92:95]
	v_mfma_f32_16x16x32_bf16 v[88:91], v[156:159], v[206:209], v[88:91]
	s_setprio 0
	s_barrier
	s_add_i32 s36, s92, s45
	v_lshl_add_u64 v[218:219], s[72:73], 0, v[172:173]
	s_mov_b32 m0, s36
	ds_read_b128 v[160:163], v229 offset:16384
	ds_read_b128 v[164:167], v229 offset:17408
	ds_read_b128 v[186:189], v229 offset:18432
	ds_read_b128 v[190:193], v229 offset:19456
	ds_read_b128 v[194:197], v229 offset:20480
	ds_read_b128 v[198:201], v229 offset:21504
	ds_read_b128 v[202:205], v229 offset:22528
	ds_read_b128 v[206:209], v229 offset:23552
	global_load_lds_dwordx4 v[218:219], off
	s_add_i32 m0, s36, 0x2000
	s_add_u32 s36, s72, 0x80000
	v_lshl_add_u64 v[220:221], s[72:73], 0, v[176:177]
	s_addc_u32 s37, s73, 0
	s_add_i32 s42, s93, s45
	global_load_lds_dwordx4 v[220:221], off
	v_lshl_add_u64 v[210:211], s[36:37], 0, v[172:173]
	s_mov_b32 m0, s42
	v_lshl_add_u64 v[232:233], s[74:75], 0, v[170:171]
	global_load_lds_dwordx4 v[210:211], off
	v_lshl_add_u64 v[210:211], s[36:37], 0, v[176:177]
	s_add_i32 m0, s42, 0x2000
	v_lshl_add_u64 v[234:235], s[74:75], 0, v[174:175]
	global_load_lds_dwordx4 v[210:211], off
	s_mov_b32 m0, s47
	s_nop 0
	global_load_lds_dwordx4 v[232:233], off
	s_mov_b32 m0, s76
	s_nop 0
	global_load_lds_dwordx4 v[234:235], off
	s_waitcnt vmcnt(8)
	s_waitcnt lgkmcnt(0)
	s_setprio 1
	s_barrier
; #define PG8_STAGE(bufoff, gbase, voff) do { _Pragma("unroll") for (int _i = 0; _i < 2; ++_i) \
;         __builtin_amdgcn_global_load_lds((const unsigned*)((const char*)(gbase) + (voff)[_i]), (LAS unsigned*)(lds + (bufoff) + ldsw + _i * 8192), 16, 0, 0); } while (0)
; #define PG8_LDA(dst, b, h) do { _Pragma("unroll") for (int m = 0; m < 4; ++m) _Pragma("unroll") for (int k = 0; k < 2; ++k) dst[m][k] = *(const LAS bf16x8*)(lds + PG8_SA(b, h) + aoff + m * 2048 + k * 1024); } while (0)
; #define PG8_LDB(dst, b, h) do { _Pragma("unroll") for (int n = 0; n < 2; ++n) _Pragma("unroll") for (int k = 0; k < 2; ++k) dst[n][k] = *(const LAS bf16x8*)(lds + PG8_SB(b, h) + boff + n * 2048 + k * 1024); } while (0)
; #define PG8_MMA(ai, bj, At, Bt) do { __builtin_amdgcn_s_setprio(1); _Pragma("unroll") for (int m = 0; m < 4; ++m) _Pragma("unroll") for (int n = 0; n < 2; ++n) _Pragma("unroll") for (int k = 0; k < 2; ++k) \
;         acc[ai][bj][m][n] = __builtin_amdgcn_mfma_f32_16x16x32_bf16(Bt[n][k], At[m][k], acc[ai][bj][m][n], 0, 0, 0); __builtin_amdgcn_s_setprio(0); } while (0)
; #define PG8_WAIT_V(n) asm volatile("s_waitcnt vmcnt(" #n ")" ::: "memory")
; #define PG8_WAIT_L(n) asm volatile("s_waitcnt lgkmcnt(" #n ")" ::: "memory")
; #define PG8_BAR __builtin_amdgcn_s_barrier()
; #define PG8_SCHED __builtin_amdgcn_sched_barrier(0)
; template <class Epi, class Sched>
; __device__ __forceinline__ void gemm_phase(LAS unsigned char* lds, const int K, const Sched& S, const Epi& E) {
;     ...
;             PG8_WAIT_V(8); PG8_WAIT_L(0); PG8_BAR; PG8_MMA(1, 0, At, B0); PG8_MMA(1, 1, At, B1); PG8_BAR; PG8_SCHED;
;             PG8_LDB(B0, 1, 0); PG8_LDB(B1, 1, 1); PG8_SCHED; PG8_LDA(At, 1, 0); PG8_STAGE(PG8_SA(0, 1), a2 + hstep, voffA);
;             PG8_WAIT_V(8); PG8_WAIT_L(0); PG8_BAR; PG8_MMA(0, 0, At, B0); PG8_MMA(0, 1, At, B1); PG8_BAR; PG8_SCHED;
	v_mfma_f32_16x16x32_bf16 v[84:87], v[0:3], v[160:163], v[84:87]
	v_mfma_f32_16x16x32_bf16 v[80:83], v[8:11], v[160:163], v[80:83]
	v_mfma_f32_16x16x32_bf16 v[68:71], v[0:3], v[186:189], v[68:71]
	v_mfma_f32_16x16x32_bf16 v[64:67], v[8:11], v[186:189], v[64:67]
	v_mfma_f32_16x16x32_bf16 v[52:55], v[0:3], v[194:197], v[52:55]
	v_mfma_f32_16x16x32_bf16 v[48:51], v[8:11], v[194:197], v[48:51]
	v_mfma_f32_16x16x32_bf16 v[0:3], v[0:3], v[202:205], v[36:39]
	v_mfma_f32_16x16x32_bf16 v[84:87], v[4:7], v[164:167], v[84:87]
	v_mfma_f32_16x16x32_bf16 v[80:83], v[12:15], v[164:167], v[80:83]
	v_mfma_f32_16x16x32_bf16 v[68:71], v[4:7], v[190:193], v[68:71]
	v_mfma_f32_16x16x32_bf16 v[64:67], v[12:15], v[190:193], v[64:67]
	v_mfma_f32_16x16x32_bf16 v[52:55], v[4:7], v[198:201], v[52:55]
	v_mfma_f32_16x16x32_bf16 v[48:51], v[12:15], v[198:201], v[48:51]
	v_mfma_f32_16x16x32_bf16 v[0:3], v[4:7], v[206:209], v[0:3]
	v_mfma_f32_16x16x32_bf16 v[4:7], v[8:11], v[202:205], v[32:35]
	v_mfma_f32_16x16x32_bf16 v[4:7], v[12:15], v[206:209], v[4:7]
	v_mfma_f32_16x16x32_bf16 v[32:35], v[16:19], v[186:189], v[60:63]
	v_mfma_f32_16x16x32_bf16 v[60:63], v[20:23], v[190:193], v[32:35]
	v_mfma_f32_16x16x32_bf16 v[32:35], v[152:155], v[186:189], v[56:59]
	v_mfma_f32_16x16x32_bf16 v[56:59], v[156:159], v[190:193], v[32:35]
	v_mfma_f32_16x16x32_bf16 v[32:35], v[16:19], v[194:197], v[44:47]
	v_mfma_f32_16x16x32_bf16 v[8:11], v[16:19], v[160:163], v[76:79]
	v_mfma_f32_16x16x32_bf16 v[44:47], v[20:23], v[198:201], v[32:35]
	v_mfma_f32_16x16x32_bf16 v[32:35], v[152:155], v[194:197], v[40:43]
	v_mfma_f32_16x16x32_bf16 v[16:19], v[16:19], v[202:205], v[28:31]
	v_mfma_f32_16x16x32_bf16 v[8:11], v[20:23], v[164:167], v[8:11]
	v_mfma_f32_16x16x32_bf16 v[12:15], v[152:155], v[160:163], v[72:75]
	v_mfma_f32_16x16x32_bf16 v[40:43], v[156:159], v[198:201], v[32:35]
	v_mfma_f32_16x16x32_bf16 v[16:19], v[20:23], v[206:209], v[16:19]
	v_mfma_f32_16x16x32_bf16 v[20:23], v[152:155], v[202:205], v[24:27]
	v_mfma_f32_16x16x32_bf16 v[12:15], v[156:159], v[164:167], v[12:15]
	v_mfma_f32_16x16x32_bf16 v[20:23], v[156:159], v[206:209], v[20:23]
	s_setprio 0
	s_barrier
	s_add_i32 s42, 0, 0x18000
	v_add_u32_e32 v36, s42, v226
	s_add_i32 s43, 0, 0x1c000
	ds_read_b128 v[24:27], v36
	ds_read_b128 v[28:31], v36 offset:1024
	ds_read_b128 v[32:35], v36 offset:2048
	ds_read_b128 v[72:75], v36 offset:3072
	v_add_u32_e32 v36, s43, v226
	ds_read_b128 v[152:155], v36
	ds_read_b128 v[156:159], v36 offset:1024
	ds_read_b128 v[160:163], v36 offset:2048
	ds_read_b128 v[164:167], v36 offset:3072
	s_add_u32 s36, s74, 0x80000
	s_addc_u32 s37, s75, 0
	s_mov_b32 m0, s77
	v_lshl_add_u64 v[210:211], s[36:37], 0, v[170:171]
	ds_read_b128 v[36:39], v229 offset:32768
	ds_read_b128 v[76:79], v229 offset:33792
	ds_read_b128 v[186:189], v229 offset:34816
	ds_read_b128 v[190:193], v229 offset:35840
	ds_read_b128 v[194:197], v229 offset:36864
	ds_read_b128 v[198:201], v229 offset:37888
	ds_read_b128 v[202:205], v229 offset:38912
	ds_read_b128 v[206:209], v229 offset:39936
	global_load_lds_dwordx4 v[210:211], off
	v_lshl_add_u64 v[210:211], s[36:37], 0, v[174:175]
	s_mov_b32 m0, s78
	s_nop 0
	global_load_lds_dwordx4 v[210:211], off
	s_waitcnt vmcnt(8)
	s_waitcnt lgkmcnt(0)
	s_setprio 1
	s_barrier
	v_mfma_f32_16x16x32_bf16 v[148:151], v[24:27], v[36:39], v[148:151]
	v_mfma_f32_16x16x32_bf16 v[144:147], v[32:35], v[36:39], v[144:147]
	v_mfma_f32_16x16x32_bf16 v[132:135], v[24:27], v[186:189], v[132:135]
	v_mfma_f32_16x16x32_bf16 v[128:131], v[32:35], v[186:189], v[128:131]
	v_mfma_f32_16x16x32_bf16 v[116:119], v[24:27], v[194:197], v[116:119]
	v_mfma_f32_16x16x32_bf16 v[112:115], v[32:35], v[194:197], v[112:115]
	v_mfma_f32_16x16x32_bf16 v[100:103], v[24:27], v[202:205], v[100:103]
	v_mfma_f32_16x16x32_bf16 v[96:99], v[32:35], v[202:205], v[96:99]
	v_mfma_f32_16x16x32_bf16 v[148:151], v[28:31], v[76:79], v[148:151]
	v_mfma_f32_16x16x32_bf16 v[144:147], v[72:75], v[76:79], v[144:147]
	v_mfma_f32_16x16x32_bf16 v[132:135], v[28:31], v[190:193], v[132:135]
	v_mfma_f32_16x16x32_bf16 v[128:131], v[72:75], v[190:193], v[128:131]
	v_mfma_f32_16x16x32_bf16 v[116:119], v[28:31], v[198:201], v[116:119]
	v_mfma_f32_16x16x32_bf16 v[112:115], v[72:75], v[198:201], v[112:115]
	v_mfma_f32_16x16x32_bf16 v[100:103], v[28:31], v[206:209], v[100:103]
	v_mfma_f32_16x16x32_bf16 v[96:99], v[72:75], v[206:209], v[96:99]
	v_mfma_f32_16x16x32_bf16 v[140:143], v[152:155], v[36:39], v[140:143]
	v_mfma_f32_16x16x32_bf16 v[36:39], v[160:163], v[36:39], v[136:139]
	v_mfma_f32_16x16x32_bf16 v[136:139], v[164:167], v[76:79], v[36:39]
	v_mfma_f32_16x16x32_bf16 v[36:39], v[152:155], v[186:189], v[124:127]
	v_mfma_f32_16x16x32_bf16 v[124:127], v[156:159], v[190:193], v[36:39]
	v_mfma_f32_16x16x32_bf16 v[36:39], v[160:163], v[186:189], v[120:123]
	v_mfma_f32_16x16x32_bf16 v[120:123], v[164:167], v[190:193], v[36:39]
	v_mfma_f32_16x16x32_bf16 v[36:39], v[152:155], v[194:197], v[108:111]
	v_mfma_f32_16x16x32_bf16 v[108:111], v[156:159], v[198:201], v[36:39]
	v_mfma_f32_16x16x32_bf16 v[36:39], v[160:163], v[194:197], v[104:107]
	v_mfma_f32_16x16x32_bf16 v[104:107], v[164:167], v[198:201], v[36:39]
	v_mfma_f32_16x16x32_bf16 v[36:39], v[152:155], v[202:205], v[92:95]
	v_mfma_f32_16x16x32_bf16 v[92:95], v[156:159], v[206:209], v[36:39]
	v_mfma_f32_16x16x32_bf16 v[36:39], v[160:163], v[202:205], v[88:91]
	v_mfma_f32_16x16x32_bf16 v[140:143], v[156:159], v[76:79], v[140:143]
	v_mfma_f32_16x16x32_bf16 v[88:91], v[164:167], v[206:209], v[36:39]
	s_setprio 0
	s_barrier
; #define PG8_STAGE(bufoff, gbase, voff) do { _Pragma("unroll") for (int _i = 0; _i < 2; ++_i) \
;         __builtin_amdgcn_global_load_lds((const unsigned*)((const char*)(gbase) + (voff)[_i]), (LAS unsigned*)(lds + (bufoff) + ldsw + _i * 8192), 16, 0, 0); } while (0)
; #define PG8_LDA(dst, b, h) do { _Pragma("unroll") for (int m = 0; m < 4; ++m) _Pragma("unroll") for (int k = 0; k < 2; ++k) dst[m][k] = *(const LAS bf16x8*)(lds + PG8_SA(b, h) + aoff + m * 2048 + k * 1024); } while (0)
; #define PG8_MMA(ai, bj, At, Bt) do { __builtin_amdgcn_s_setprio(1); _Pragma("unroll") for (int m = 0; m < 4; ++m) _Pragma("unroll") for (int n = 0; n < 2; ++n) _Pragma("unroll") for (int k = 0; k < 2; ++k) \
;         acc[ai][bj][m][n] = __builtin_amdgcn_mfma_f32_16x16x32_bf16(Bt[n][k], At[m][k], acc[ai][bj][m][n], 0, 0, 0); __builtin_amdgcn_s_setprio(0); } while (0)
; #define PG8_WAIT_V(n) asm volatile("s_waitcnt vmcnt(" #n ")" ::: "memory")
; #define PG8_WAIT_L(n) asm volatile("s_waitcnt lgkmcnt(" #n ")" ::: "memory")
; #define PG8_BAR __builtin_amdgcn_s_barrier()
; #define PG8_SCHED __builtin_amdgcn_sched_barrier(0)
; template <class Epi, class Sched>
; __device__ __forceinline__ void gemm_phase(LAS unsigned char* lds, const int K, const Sched& S, const Epi& E) {
;     ...
;             PG8_LDA(At, 1, 1); PG8_STAGE(PG8_SB(1, 0), b3, voffB); PG8_STAGE(PG8_SB(1, 1), b3 + hstep, voffB); PG8_STAGE(PG8_SA(1, 0), a3, voffA);
;             PG8_WAIT_V(8); PG8_WAIT_L(0); PG8_BAR; PG8_MMA(1, 0, At, B0); PG8_MMA(1, 1, At, B1); PG8_BAR; PG8_SCHED;
;         }
;         if (wr == 0) PG8_BAR;
	s_add_i32 s36, s42, s45
	s_nop 2
	v_lshl_add_u64 v[36:37], v[218:219], 0, s[30:31]
	s_mov_b32 m0, s36
	ds_read_b128 v[186:189], v229 offset:49152
	ds_read_b128 v[190:193], v229 offset:50176
	ds_read_b128 v[194:197], v229 offset:51200
	ds_read_b128 v[198:201], v229 offset:52224
	ds_read_b128 v[202:205], v229 offset:53248
	ds_read_b128 v[206:209], v229 offset:54272
	ds_read_b128 v[210:213], v229 offset:55296
	ds_read_b128 v[214:217], v229 offset:56320
	global_load_lds_dwordx4 v[36:37], off
	s_add_i32 m0, s36, 0x2000
	s_add_u32 s36, s72, 0x80080
	v_lshl_add_u64 v[36:37], v[220:221], 0, s[30:31]
	s_addc_u32 s37, s73, 0
	s_add_i32 s42, s43, s45
	global_load_lds_dwordx4 v[36:37], off
	v_lshl_add_u64 v[36:37], s[36:37], 0, v[172:173]
	s_mov_b32 m0, s42
	s_nop 0
	global_load_lds_dwordx4 v[36:37], off
	v_lshl_add_u64 v[36:37], s[36:37], 0, v[176:177]
	s_add_i32 m0, s42, 0x2000
	s_nop 0
	global_load_lds_dwordx4 v[36:37], off
	v_lshl_add_u64 v[36:37], v[232:233], 0, s[30:31]
	s_mov_b32 m0, s82
	s_nop 0
	global_load_lds_dwordx4 v[36:37], off
	v_lshl_add_u64 v[36:37], v[234:235], 0, s[30:31]
	s_mov_b32 m0, s83
	s_nop 0
	global_load_lds_dwordx4 v[36:37], off
	s_waitcnt vmcnt(8)
	s_waitcnt lgkmcnt(0)
	s_setprio 1
	s_barrier
	v_mfma_f32_16x16x32_bf16 v[36:39], v[24:27], v[186:189], v[84:87]
	v_mfma_f32_16x16x32_bf16 v[84:87], v[28:31], v[190:193], v[36:39]
	v_mfma_f32_16x16x32_bf16 v[36:39], v[32:35], v[186:189], v[80:83]
	v_mfma_f32_16x16x32_bf16 v[80:83], v[72:75], v[190:193], v[36:39]
	v_mfma_f32_16x16x32_bf16 v[36:39], v[24:27], v[194:197], v[68:71]
	v_mfma_f32_16x16x32_bf16 v[68:71], v[28:31], v[198:201], v[36:39]
	v_mfma_f32_16x16x32_bf16 v[36:39], v[32:35], v[194:197], v[64:67]
	v_mfma_f32_16x16x32_bf16 v[64:67], v[72:75], v[198:201], v[36:39]
	v_mfma_f32_16x16x32_bf16 v[36:39], v[24:27], v[202:205], v[52:55]
	v_mfma_f32_16x16x32_bf16 v[52:55], v[28:31], v[206:209], v[36:39]
	v_mfma_f32_16x16x32_bf16 v[36:39], v[32:35], v[202:205], v[48:51]
	v_mfma_f32_16x16x32_bf16 v[0:3], v[24:27], v[210:213], v[0:3]
	v_mfma_f32_16x16x32_bf16 v[48:51], v[72:75], v[206:209], v[36:39]
	v_mfma_f32_16x16x32_bf16 v[36:39], v[28:31], v[214:217], v[0:3]
	v_mfma_f32_16x16x32_bf16 v[0:3], v[32:35], v[210:213], v[4:7]
	v_mfma_f32_16x16x32_bf16 v[32:35], v[72:75], v[214:217], v[0:3]
	v_mfma_f32_16x16x32_bf16 v[0:3], v[152:155], v[186:189], v[8:11]
	v_mfma_f32_16x16x32_bf16 v[76:79], v[156:159], v[190:193], v[0:3]
	v_mfma_f32_16x16x32_bf16 v[0:3], v[160:163], v[186:189], v[12:15]
	v_mfma_f32_16x16x32_bf16 v[72:75], v[164:167], v[190:193], v[0:3]
	v_mfma_f32_16x16x32_bf16 v[0:3], v[152:155], v[194:197], v[60:63]
	v_mfma_f32_16x16x32_bf16 v[60:63], v[156:159], v[198:201], v[0:3]
	v_mfma_f32_16x16x32_bf16 v[0:3], v[160:163], v[194:197], v[56:59]
	v_mfma_f32_16x16x32_bf16 v[56:59], v[164:167], v[198:201], v[0:3]
	v_mfma_f32_16x16x32_bf16 v[0:3], v[152:155], v[202:205], v[44:47]
	v_mfma_f32_16x16x32_bf16 v[44:47], v[156:159], v[206:209], v[0:3]
	v_mfma_f32_16x16x32_bf16 v[0:3], v[160:163], v[202:205], v[40:43]
	v_mfma_f32_16x16x32_bf16 v[40:43], v[164:167], v[206:209], v[0:3]
	v_mfma_f32_16x16x32_bf16 v[0:3], v[152:155], v[210:213], v[16:19]
	v_mfma_f32_16x16x32_bf16 v[28:31], v[156:159], v[214:217], v[0:3]
	v_mfma_f32_16x16x32_bf16 v[0:3], v[160:163], v[210:213], v[20:23]
	v_mfma_f32_16x16x32_bf16 v[24:27], v[164:167], v[214:217], v[0:3]
	s_setprio 0
	s_barrier
	s_add_i32 s9, s9, 2
	s_add_u32 s6, s6, 0x100
	s_addc_u32 s7, s7, 0
	s_add_u32 s1, s1, 0x100
	s_addc_u32 s8, s8, 0
	s_cmp_gt_u32 s9, 29
	s_cbranch_scc0 .LBB0_661
	s_and_b64 vcc, exec, s[34:35]
	s_cbranch_vccz .LBB0_664
	s_barrier

; #define PG8_STAGE(bufoff, gbase, voff) do { _Pragma("unroll") for (int _i = 0; _i < 2; ++_i) \
;         __builtin_amdgcn_global_load_lds((const unsigned*)((const char*)(gbase) + (voff)[_i]), (LAS unsigned*)(lds + (bufoff) + ldsw + _i * 8192), 16, 0, 0); } while (0)
; #define PG8_LDA(dst, b, h) do { _Pragma("unroll") for (int m = 0; m < 4; ++m) _Pragma("unroll") for (int k = 0; k < 2; ++k) dst[m][k] = *(const LAS bf16x8*)(lds + PG8_SA(b, h) + aoff + m * 2048 + k * 1024); } while (0)
; #define PG8_LDB(dst, b, h) do { _Pragma("unroll") for (int n = 0; n < 2; ++n) _Pragma("unroll") for (int k = 0; k < 2; ++k) dst[n][k] = *(const LAS bf16x8*)(lds + PG8_SB(b, h) + boff + n * 2048 + k * 1024); } while (0)
; #define PG8_MMA(ai, bj, At, Bt) do { __builtin_amdgcn_s_setprio(1); _Pragma("unroll") for (int m = 0; m < 4; ++m) _Pragma("unroll") for (int n = 0; n < 2; ++n) _Pragma("unroll") for (int k = 0; k < 2; ++k) \
;         acc[ai][bj][m][n] = __builtin_amdgcn_mfma_f32_16x16x32_bf16(Bt[n][k], At[m][k], acc[ai][bj][m][n], 0, 0, 0); __builtin_amdgcn_s_setprio(0); } while (0)
; #define PG8_WAIT_V(n) asm volatile("s_waitcnt vmcnt(" #n ")" ::: "memory")
; #define PG8_WAIT_L(n) asm volatile("s_waitcnt lgkmcnt(" #n ")" ::: "memory")
; #define PG8_BAR __builtin_amdgcn_s_barrier()
; #define PG8_SCHED __builtin_amdgcn_sched_barrier(0)
; template <class Epi, class Sched>
; __device__ __forceinline__ void gemm_phase(LAS unsigned char* lds, const int K, const Sched& S, const Epi& E) {
;     ...
;             const char* a1 = cA + (size_t)(t + 1) * kstep;
;             const char* a2 = last ? nA : cA + (size_t)(t + 2) * kstep; const char* b2 = last ? nB : cB + (size_t)(t + 2) * kstep;
;             const char* a3 = a2 + kstep; const char* b3 = b2 + kstep;
;             PG8_LDB(B0, 0, 0); PG8_LDB(B1, 0, 1); PG8_SCHED; PG8_LDA(At, 0, 0); PG8_STAGE(PG8_SA(1, 1), a1 + hstep, voffA);
;             PG8_WAIT_V(8); PG8_WAIT_L(0); PG8_BAR; PG8_MMA(0, 0, At, B0); PG8_MMA(0, 1, At, B1); PG8_BAR; PG8_SCHED;
;             PG8_LDA(At, 0, 1); PG8_STAGE(PG8_SB(0, 0), b2, voffB); PG8_STAGE(PG8_SB(0, 1), b2 + hstep, voffB); PG8_STAGE(PG8_SA(0, 0), a2, voffA);
;             PG8_WAIT_V(8); PG8_WAIT_L(0); PG8_BAR; PG8_MMA(1, 0, At, B0); PG8_MMA(1, 1, At, B1); PG8_BAR; PG8_SCHED;
.LBB0_1341:
	ds_read_b128 v[140:143], v147
	ds_read_b128 v[152:155], v147 offset:1024
	ds_read_b128 v[156:159], v147 offset:2048
	ds_read_b128 v[160:163], v147 offset:3072
	ds_read_b128 v[164:167], v148
	ds_read_b128 v[168:171], v148 offset:1024
	ds_read_b128 v[172:175], v148 offset:2048
	ds_read_b128 v[176:179], v148 offset:3072
	s_add_u32 s19, s34, 0xfff80080
	s_addc_u32 s36, s35, -1
	s_cmp_eq_u32 s17, 28
	s_cselect_b32 s39, s23, s36
	s_cselect_b32 s38, s22, s19
	s_cselect_b32 s37, s25, s9
	s_cselect_b32 s36, s24, s8
	v_lshl_add_u64 v[212:213], s[34:35], 0, v[136:137]
	s_add_i32 m0, s27, 0xc000
	ds_read_b128 v[180:183], v149
	ds_read_b128 v[184:187], v149 offset:1024
	ds_read_b128 v[188:191], v149 offset:2048
	ds_read_b128 v[192:195], v149 offset:3072
	ds_read_b128 v[196:199], v149 offset:4096
	ds_read_b128 v[200:203], v149 offset:5120
	ds_read_b128 v[204:207], v149 offset:6144
	ds_read_b128 v[208:211], v149 offset:7168
	global_load_lds_dwordx4 v[212:213], off
	v_lshl_add_u64 v[212:213], s[34:35], 0, v[138:139]
	s_add_i32 m0, s27, 0xe000
	s_nop 0
	global_load_lds_dwordx4 v[212:213], off
	s_waitcnt vmcnt(8)
	s_waitcnt lgkmcnt(0)
	s_setprio 1
	s_barrier
	v_mfma_f32_16x16x32_bf16 v[124:127], v[140:143], v[180:183], v[124:127]
	v_mfma_f32_16x16x32_bf16 v[120:123], v[156:159], v[180:183], v[120:123]
	v_mfma_f32_16x16x32_bf16 v[108:111], v[140:143], v[188:191], v[108:111]
	v_mfma_f32_16x16x32_bf16 v[104:107], v[156:159], v[188:191], v[104:107]
	v_mfma_f32_16x16x32_bf16 v[92:95], v[140:143], v[196:199], v[92:95]
	v_mfma_f32_16x16x32_bf16 v[88:91], v[156:159], v[196:199], v[88:91]
	v_mfma_f32_16x16x32_bf16 v[76:79], v[140:143], v[204:207], v[76:79]
	v_mfma_f32_16x16x32_bf16 v[72:75], v[156:159], v[204:207], v[72:75]
	v_mfma_f32_16x16x32_bf16 v[124:127], v[152:155], v[184:187], v[124:127]
	v_mfma_f32_16x16x32_bf16 v[120:123], v[160:163], v[184:187], v[120:123]
	v_mfma_f32_16x16x32_bf16 v[108:111], v[152:155], v[192:195], v[108:111]
	v_mfma_f32_16x16x32_bf16 v[104:107], v[160:163], v[192:195], v[104:107]
	v_mfma_f32_16x16x32_bf16 v[92:95], v[152:155], v[200:203], v[92:95]
	v_mfma_f32_16x16x32_bf16 v[88:91], v[160:163], v[200:203], v[88:91]
	v_mfma_f32_16x16x32_bf16 v[76:79], v[152:155], v[208:211], v[76:79]
	v_mfma_f32_16x16x32_bf16 v[72:75], v[160:163], v[208:211], v[72:75]
	v_mfma_f32_16x16x32_bf16 v[116:119], v[164:167], v[180:183], v[116:119]
	v_mfma_f32_16x16x32_bf16 v[112:115], v[172:175], v[180:183], v[112:115]
	v_mfma_f32_16x16x32_bf16 v[100:103], v[164:167], v[188:191], v[100:103]
	v_mfma_f32_16x16x32_bf16 v[96:99], v[172:175], v[188:191], v[96:99]
	v_mfma_f32_16x16x32_bf16 v[84:87], v[164:167], v[196:199], v[84:87]
	v_mfma_f32_16x16x32_bf16 v[80:83], v[172:175], v[196:199], v[80:83]
	v_mfma_f32_16x16x32_bf16 v[68:71], v[164:167], v[204:207], v[68:71]
	v_mfma_f32_16x16x32_bf16 v[64:67], v[172:175], v[204:207], v[64:67]
	v_mfma_f32_16x16x32_bf16 v[116:119], v[168:171], v[184:187], v[116:119]
	v_mfma_f32_16x16x32_bf16 v[112:115], v[176:179], v[184:187], v[112:115]
	v_mfma_f32_16x16x32_bf16 v[100:103], v[168:171], v[192:195], v[100:103]
	v_mfma_f32_16x16x32_bf16 v[96:99], v[176:179], v[192:195], v[96:99]
	v_mfma_f32_16x16x32_bf16 v[84:87], v[168:171], v[200:203], v[84:87]
	v_mfma_f32_16x16x32_bf16 v[80:83], v[176:179], v[200:203], v[80:83]
	v_mfma_f32_16x16x32_bf16 v[68:71], v[168:171], v[208:211], v[68:71]
	v_mfma_f32_16x16x32_bf16 v[64:67], v[176:179], v[208:211], v[64:67]
	s_setprio 0
	s_barrier
	s_add_i32 s19, s48, s40
	v_lshl_add_u64 v[212:213], s[36:37], 0, v[130:131]
	s_mov_b32 m0, s19
	ds_read_b128 v[180:183], v149 offset:16384
	ds_read_b128 v[184:187], v149 offset:17408
	ds_read_b128 v[188:191], v149 offset:18432
	ds_read_b128 v[192:195], v149 offset:19456
	ds_read_b128 v[196:199], v149 offset:20480
	ds_read_b128 v[200:203], v149 offset:21504
	ds_read_b128 v[204:207], v149 offset:22528
	ds_read_b128 v[208:211], v149 offset:23552
	global_load_lds_dwordx4 v[212:213], off
	s_add_i32 m0, s19, 0x2000
	s_add_u32 s50, s36, 0x80000
	v_lshl_add_u64 v[214:215], s[36:37], 0, v[134:135]
	s_addc_u32 s51, s37, 0
	s_add_i32 s19, s49, s40
	global_load_lds_dwordx4 v[214:215], off
	v_lshl_add_u64 v[216:217], s[50:51], 0, v[130:131]
	s_mov_b32 m0, s19
	v_lshl_add_u64 v[218:219], s[38:39], 0, v[132:133]
	global_load_lds_dwordx4 v[216:217], off
	v_lshl_add_u64 v[216:217], s[50:51], 0, v[134:135]
	s_add_i32 m0, s19, 0x2000
	s_nop 0
	global_load_lds_dwordx4 v[216:217], off
	v_lshl_add_u64 v[216:217], s[38:39], 0, v[128:129]
	s_mov_b32 m0, s27
	s_nop 0
	global_load_lds_dwordx4 v[216:217], off
	s_mov_b32 m0, s31
	s_nop 0
	global_load_lds_dwordx4 v[218:219], off
	s_waitcnt vmcnt(8)
	s_waitcnt lgkmcnt(0)
	s_setprio 1
	s_barrier
; #define PG8_STAGE(bufoff, gbase, voff) do { _Pragma("unroll") for (int _i = 0; _i < 2; ++_i) \
;         __builtin_amdgcn_global_load_lds((const unsigned*)((const char*)(gbase) + (voff)[_i]), (LAS unsigned*)(lds + (bufoff) + ldsw + _i * 8192), 16, 0, 0); } while (0)
; #define PG8_LDA(dst, b, h) do { _Pragma("unroll") for (int m = 0; m < 4; ++m) _Pragma("unroll") for (int k = 0; k < 2; ++k) dst[m][k] = *(const LAS bf16x8*)(lds + PG8_SA(b, h) + aoff + m * 2048 + k * 1024); } while (0)
; #define PG8_LDB(dst, b, h) do { _Pragma("unroll") for (int n = 0; n < 2; ++n) _Pragma("unroll") for (int k = 0; k < 2; ++k) dst[n][k] = *(const LAS bf16x8*)(lds + PG8_SB(b, h) + boff + n * 2048 + k * 1024); } while (0)
; #define PG8_MMA(ai, bj, At, Bt) do { __builtin_amdgcn_s_setprio(1); _Pragma("unroll") for (int m = 0; m < 4; ++m) _Pragma("unroll") for (int n = 0; n < 2; ++n) _Pragma("unroll") for (int k = 0; k < 2; ++k) \
;         acc[ai][bj][m][n] = __builtin_amdgcn_mfma_f32_16x16x32_bf16(Bt[n][k], At[m][k], acc[ai][bj][m][n], 0, 0, 0); __builtin_amdgcn_s_setprio(0); } while (0)
; #define PG8_WAIT_V(n) asm volatile("s_waitcnt vmcnt(" #n ")" ::: "memory")
; #define PG8_WAIT_L(n) asm volatile("s_waitcnt lgkmcnt(" #n ")" ::: "memory")
; #define PG8_BAR __builtin_amdgcn_s_barrier()
; #define PG8_SCHED __builtin_amdgcn_sched_barrier(0)
; template <class Epi, class Sched>
; __device__ __forceinline__ void gemm_phase(LAS unsigned char* lds, const int K, const Sched& S, const Epi& E) {
;     ...
;             PG8_WAIT_V(8); PG8_WAIT_L(0); PG8_BAR; PG8_MMA(1, 0, At, B0); PG8_MMA(1, 1, At, B1); PG8_BAR; PG8_SCHED;
;             PG8_LDB(B0, 1, 0); PG8_LDB(B1, 1, 1); PG8_SCHED; PG8_LDA(At, 1, 0); PG8_STAGE(PG8_SA(0, 1), a2 + hstep, voffA);
;             PG8_WAIT_V(8); PG8_WAIT_L(0); PG8_BAR; PG8_MMA(0, 0, At, B0); PG8_MMA(0, 1, At, B1); PG8_BAR; PG8_SCHED;
	v_mfma_f32_16x16x32_bf16 v[60:63], v[140:143], v[180:183], v[60:63]
	v_mfma_f32_16x16x32_bf16 v[56:59], v[156:159], v[180:183], v[56:59]
	v_mfma_f32_16x16x32_bf16 v[44:47], v[140:143], v[188:191], v[44:47]
	v_mfma_f32_16x16x32_bf16 v[40:43], v[156:159], v[188:191], v[40:43]
	v_mfma_f32_16x16x32_bf16 v[28:31], v[140:143], v[196:199], v[28:31]
	v_mfma_f32_16x16x32_bf16 v[24:27], v[156:159], v[196:199], v[24:27]
	v_mfma_f32_16x16x32_bf16 v[12:15], v[140:143], v[204:207], v[12:15]
	v_mfma_f32_16x16x32_bf16 v[8:11], v[156:159], v[204:207], v[8:11]
	v_mfma_f32_16x16x32_bf16 v[60:63], v[152:155], v[184:187], v[60:63]
	v_mfma_f32_16x16x32_bf16 v[56:59], v[160:163], v[184:187], v[56:59]
	v_mfma_f32_16x16x32_bf16 v[44:47], v[152:155], v[192:195], v[44:47]
	v_mfma_f32_16x16x32_bf16 v[40:43], v[160:163], v[192:195], v[40:43]
	v_mfma_f32_16x16x32_bf16 v[28:31], v[152:155], v[200:203], v[28:31]
	v_mfma_f32_16x16x32_bf16 v[24:27], v[160:163], v[200:203], v[24:27]
	v_mfma_f32_16x16x32_bf16 v[12:15], v[152:155], v[208:211], v[12:15]
	v_mfma_f32_16x16x32_bf16 v[8:11], v[160:163], v[208:211], v[8:11]
	v_mfma_f32_16x16x32_bf16 v[52:55], v[164:167], v[180:183], v[52:55]
	v_mfma_f32_16x16x32_bf16 v[48:51], v[172:175], v[180:183], v[48:51]
	v_mfma_f32_16x16x32_bf16 v[36:39], v[164:167], v[188:191], v[36:39]
	v_mfma_f32_16x16x32_bf16 v[32:35], v[172:175], v[188:191], v[32:35]
	v_mfma_f32_16x16x32_bf16 v[20:23], v[164:167], v[196:199], v[20:23]
	v_mfma_f32_16x16x32_bf16 v[16:19], v[172:175], v[196:199], v[16:19]
	v_mfma_f32_16x16x32_bf16 v[4:7], v[164:167], v[204:207], v[4:7]
	v_mfma_f32_16x16x32_bf16 v[0:3], v[172:175], v[204:207], v[0:3]
	v_mfma_f32_16x16x32_bf16 v[52:55], v[168:171], v[184:187], v[52:55]
	v_mfma_f32_16x16x32_bf16 v[48:51], v[176:179], v[184:187], v[48:51]
	v_mfma_f32_16x16x32_bf16 v[36:39], v[168:171], v[192:195], v[36:39]
	v_mfma_f32_16x16x32_bf16 v[32:35], v[176:179], v[192:195], v[32:35]
	v_mfma_f32_16x16x32_bf16 v[20:23], v[168:171], v[200:203], v[20:23]
	v_mfma_f32_16x16x32_bf16 v[16:19], v[176:179], v[200:203], v[16:19]
	v_mfma_f32_16x16x32_bf16 v[4:7], v[168:171], v[208:211], v[4:7]
	v_mfma_f32_16x16x32_bf16 v[0:3], v[176:179], v[208:211], v[0:3]
	s_setprio 0
	s_barrier
	s_add_i32 s19, 0, 0x18000
	v_add_u32_e32 v151, s19, v146
	s_add_i32 s50, 0, 0x1c000
	ds_read_b128 v[140:143], v151
	ds_read_b128 v[152:155], v151 offset:1024
	ds_read_b128 v[156:159], v151 offset:2048
	ds_read_b128 v[160:163], v151 offset:3072
	v_add_u32_e32 v151, s50, v146
	ds_read_b128 v[164:167], v151
	ds_read_b128 v[168:171], v151 offset:1024
	ds_read_b128 v[172:175], v151 offset:2048
	ds_read_b128 v[176:179], v151 offset:3072
	s_add_u32 s38, s38, 0x80000
	s_addc_u32 s39, s39, 0
	s_mov_b32 m0, s41
	v_lshl_add_u64 v[220:221], s[38:39], 0, v[128:129]
	ds_read_b128 v[180:183], v149 offset:32768
	ds_read_b128 v[184:187], v149 offset:33792
	ds_read_b128 v[188:191], v149 offset:34816
	ds_read_b128 v[192:195], v149 offset:35840
	ds_read_b128 v[196:199], v149 offset:36864
	ds_read_b128 v[200:203], v149 offset:37888
	ds_read_b128 v[204:207], v149 offset:38912
	ds_read_b128 v[208:211], v149 offset:39936
	global_load_lds_dwordx4 v[220:221], off
	v_lshl_add_u64 v[220:221], s[38:39], 0, v[132:133]
	s_mov_b32 m0, s42
	s_nop 0
	global_load_lds_dwordx4 v[220:221], off
	s_waitcnt vmcnt(8)
	s_waitcnt lgkmcnt(0)
	s_setprio 1
	s_barrier
	v_mfma_f32_16x16x32_bf16 v[124:127], v[140:143], v[180:183], v[124:127]
	v_mfma_f32_16x16x32_bf16 v[120:123], v[156:159], v[180:183], v[120:123]
	v_mfma_f32_16x16x32_bf16 v[108:111], v[140:143], v[188:191], v[108:111]
	v_mfma_f32_16x16x32_bf16 v[104:107], v[156:159], v[188:191], v[104:107]
	v_mfma_f32_16x16x32_bf16 v[92:95], v[140:143], v[196:199], v[92:95]
	v_mfma_f32_16x16x32_bf16 v[88:91], v[156:159], v[196:199], v[88:91]
	v_mfma_f32_16x16x32_bf16 v[76:79], v[140:143], v[204:207], v[76:79]
	v_mfma_f32_16x16x32_bf16 v[72:75], v[156:159], v[204:207], v[72:75]
	v_mfma_f32_16x16x32_bf16 v[124:127], v[152:155], v[184:187], v[124:127]
	v_mfma_f32_16x16x32_bf16 v[120:123], v[160:163], v[184:187], v[120:123]
	v_mfma_f32_16x16x32_bf16 v[108:111], v[152:155], v[192:195], v[108:111]
	v_mfma_f32_16x16x32_bf16 v[104:107], v[160:163], v[192:195], v[104:107]
	v_mfma_f32_16x16x32_bf16 v[92:95], v[152:155], v[200:203], v[92:95]
	v_mfma_f32_16x16x32_bf16 v[88:91], v[160:163], v[200:203], v[88:91]
	v_mfma_f32_16x16x32_bf16 v[76:79], v[152:155], v[208:211], v[76:79]
	v_mfma_f32_16x16x32_bf16 v[72:75], v[160:163], v[208:211], v[72:75]
	v_mfma_f32_16x16x32_bf16 v[116:119], v[164:167], v[180:183], v[116:119]
	v_mfma_f32_16x16x32_bf16 v[112:115], v[172:175], v[180:183], v[112:115]
	v_mfma_f32_16x16x32_bf16 v[100:103], v[164:167], v[188:191], v[100:103]
	v_mfma_f32_16x16x32_bf16 v[96:99], v[172:175], v[188:191], v[96:99]
	v_mfma_f32_16x16x32_bf16 v[84:87], v[164:167], v[196:199], v[84:87]
	v_mfma_f32_16x16x32_bf16 v[80:83], v[172:175], v[196:199], v[80:83]
	v_mfma_f32_16x16x32_bf16 v[68:71], v[164:167], v[204:207], v[68:71]
	v_mfma_f32_16x16x32_bf16 v[64:67], v[172:175], v[204:207], v[64:67]
	v_mfma_f32_16x16x32_bf16 v[116:119], v[168:171], v[184:187], v[116:119]
	v_mfma_f32_16x16x32_bf16 v[112:115], v[176:179], v[184:187], v[112:115]
	v_mfma_f32_16x16x32_bf16 v[100:103], v[168:171], v[192:195], v[100:103]
	v_mfma_f32_16x16x32_bf16 v[96:99], v[176:179], v[192:195], v[96:99]
	v_mfma_f32_16x16x32_bf16 v[84:87], v[168:171], v[200:203], v[84:87]
	v_mfma_f32_16x16x32_bf16 v[80:83], v[176:179], v[200:203], v[80:83]
	v_mfma_f32_16x16x32_bf16 v[68:71], v[168:171], v[208:211], v[68:71]
	v_mfma_f32_16x16x32_bf16 v[64:67], v[176:179], v[208:211], v[64:67]
	s_setprio 0
	s_barrier
; #define PG8_STAGE(bufoff, gbase, voff) do { _Pragma("unroll") for (int _i = 0; _i < 2; ++_i) \
;         __builtin_amdgcn_global_load_lds((const unsigned*)((const char*)(gbase) + (voff)[_i]), (LAS unsigned*)(lds + (bufoff) + ldsw + _i * 8192), 16, 0, 0); } while (0)
; #define PG8_LDA(dst, b, h) do { _Pragma("unroll") for (int m = 0; m < 4; ++m) _Pragma("unroll") for (int k = 0; k < 2; ++k) dst[m][k] = *(const LAS bf16x8*)(lds + PG8_SA(b, h) + aoff + m * 2048 + k * 1024); } while (0)
; #define PG8_MMA(ai, bj, At, Bt) do { __builtin_amdgcn_s_setprio(1); _Pragma("unroll") for (int m = 0; m < 4; ++m) _Pragma("unroll") for (int n = 0; n < 2; ++n) _Pragma("unroll") for (int k = 0; k < 2; ++k) \
;         acc[ai][bj][m][n] = __builtin_amdgcn_mfma_f32_16x16x32_bf16(Bt[n][k], At[m][k], acc[ai][bj][m][n], 0, 0, 0); __builtin_amdgcn_s_setprio(0); } while (0)
; #define PG8_WAIT_V(n) asm volatile("s_waitcnt vmcnt(" #n ")" ::: "memory")
; #define PG8_WAIT_L(n) asm volatile("s_waitcnt lgkmcnt(" #n ")" ::: "memory")
; #define PG8_BAR __builtin_amdgcn_s_barrier()
; #define PG8_SCHED __builtin_amdgcn_sched_barrier(0)
; template <class Epi, class Sched>
; __device__ __forceinline__ void gemm_phase(LAS unsigned char* lds, const int K, const Sched& S, const Epi& E) {
;     ...
;             PG8_LDA(At, 1, 1); PG8_STAGE(PG8_SB(1, 0), b3, voffB); PG8_STAGE(PG8_SB(1, 1), b3 + hstep, voffB); PG8_STAGE(PG8_SA(1, 0), a3, voffA);
;             PG8_WAIT_V(8); PG8_WAIT_L(0); PG8_BAR; PG8_MMA(1, 0, At, B0); PG8_MMA(1, 1, At, B1); PG8_BAR; PG8_SCHED;
;         }
;         if (wr == 0) PG8_BAR;
	s_add_i32 s19, s19, s40
	v_lshl_add_u64 v[212:213], v[212:213], 0, s[12:13]
	s_mov_b32 m0, s19
	ds_read_b128 v[180:183], v149 offset:49152
	ds_read_b128 v[184:187], v149 offset:50176
	ds_read_b128 v[188:191], v149 offset:51200
	ds_read_b128 v[192:195], v149 offset:52224
	ds_read_b128 v[196:199], v149 offset:53248
	ds_read_b128 v[200:203], v149 offset:54272
	ds_read_b128 v[204:207], v149 offset:55296
	ds_read_b128 v[208:211], v149 offset:56320
	global_load_lds_dwordx4 v[212:213], off
	s_add_i32 m0, s19, 0x2000
	s_add_u32 s36, s36, 0x80080
	v_lshl_add_u64 v[212:213], v[214:215], 0, s[12:13]
	s_addc_u32 s37, s37, 0
	s_add_i32 s19, s50, s40
	global_load_lds_dwordx4 v[212:213], off
	v_lshl_add_u64 v[212:213], s[36:37], 0, v[130:131]
	s_mov_b32 m0, s19
	s_nop 0
	global_load_lds_dwordx4 v[212:213], off
	v_lshl_add_u64 v[212:213], s[36:37], 0, v[134:135]
	s_add_i32 m0, s19, 0x2000
	s_nop 0
	global_load_lds_dwordx4 v[212:213], off
	v_lshl_add_u64 v[212:213], v[216:217], 0, s[12:13]
	s_mov_b32 m0, s46
	s_nop 0
	global_load_lds_dwordx4 v[212:213], off
	v_lshl_add_u64 v[212:213], v[218:219], 0, s[12:13]
	s_mov_b32 m0, s47
	s_nop 0
	global_load_lds_dwordx4 v[212:213], off
	s_waitcnt vmcnt(8)
	s_waitcnt lgkmcnt(0)
	s_setprio 1
	s_barrier
	v_mfma_f32_16x16x32_bf16 v[60:63], v[140:143], v[180:183], v[60:63]
	v_mfma_f32_16x16x32_bf16 v[56:59], v[156:159], v[180:183], v[56:59]
	v_mfma_f32_16x16x32_bf16 v[44:47], v[140:143], v[188:191], v[44:47]
	v_mfma_f32_16x16x32_bf16 v[40:43], v[156:159], v[188:191], v[40:43]
	v_mfma_f32_16x16x32_bf16 v[28:31], v[140:143], v[196:199], v[28:31]
	v_mfma_f32_16x16x32_bf16 v[24:27], v[156:159], v[196:199], v[24:27]
	v_mfma_f32_16x16x32_bf16 v[12:15], v[140:143], v[204:207], v[12:15]
	v_mfma_f32_16x16x32_bf16 v[8:11], v[156:159], v[204:207], v[8:11]
	v_mfma_f32_16x16x32_bf16 v[60:63], v[152:155], v[184:187], v[60:63]
	v_mfma_f32_16x16x32_bf16 v[56:59], v[160:163], v[184:187], v[56:59]
	v_mfma_f32_16x16x32_bf16 v[44:47], v[152:155], v[192:195], v[44:47]
	v_mfma_f32_16x16x32_bf16 v[40:43], v[160:163], v[192:195], v[40:43]
	v_mfma_f32_16x16x32_bf16 v[28:31], v[152:155], v[200:203], v[28:31]
	v_mfma_f32_16x16x32_bf16 v[24:27], v[160:163], v[200:203], v[24:27]
	v_mfma_f32_16x16x32_bf16 v[12:15], v[152:155], v[208:211], v[12:15]
	v_mfma_f32_16x16x32_bf16 v[8:11], v[160:163], v[208:211], v[8:11]
	v_mfma_f32_16x16x32_bf16 v[52:55], v[164:167], v[180:183], v[52:55]
	v_mfma_f32_16x16x32_bf16 v[48:51], v[172:175], v[180:183], v[48:51]
	v_mfma_f32_16x16x32_bf16 v[36:39], v[164:167], v[188:191], v[36:39]
	v_mfma_f32_16x16x32_bf16 v[32:35], v[172:175], v[188:191], v[32:35]
	v_mfma_f32_16x16x32_bf16 v[20:23], v[164:167], v[196:199], v[20:23]
	v_mfma_f32_16x16x32_bf16 v[16:19], v[172:175], v[196:199], v[16:19]
	v_mfma_f32_16x16x32_bf16 v[4:7], v[164:167], v[204:207], v[4:7]
	v_mfma_f32_16x16x32_bf16 v[0:3], v[172:175], v[204:207], v[0:3]
	v_mfma_f32_16x16x32_bf16 v[52:55], v[168:171], v[184:187], v[52:55]
	v_mfma_f32_16x16x32_bf16 v[48:51], v[176:179], v[184:187], v[48:51]
	v_mfma_f32_16x16x32_bf16 v[36:39], v[168:171], v[192:195], v[36:39]
	v_mfma_f32_16x16x32_bf16 v[32:35], v[176:179], v[192:195], v[32:35]
	v_mfma_f32_16x16x32_bf16 v[20:23], v[168:171], v[200:203], v[20:23]
	v_mfma_f32_16x16x32_bf16 v[16:19], v[176:179], v[200:203], v[16:19]
	v_mfma_f32_16x16x32_bf16 v[4:7], v[168:171], v[208:211], v[4:7]
	v_mfma_f32_16x16x32_bf16 v[0:3], v[176:179], v[208:211], v[0:3]
	s_setprio 0
	s_barrier
	s_add_i32 s17, s17, 2
	s_add_u32 s34, s34, 0x100
	s_addc_u32 s35, s35, 0
	s_add_u32 s8, s8, 0x100
	s_addc_u32 s9, s9, 0
	s_cmp_gt_u32 s17, 29
	s_cbranch_scc0 .LBB0_1341
	s_and_b64 vcc, exec, s[14:15]
	s_cbranch_vccz .LBB0_1344
	s_barrier

; #define PG8_STAGE(bufoff, gbase, voff) do { _Pragma("unroll") for (int _i = 0; _i < 2; ++_i) \
;         __builtin_amdgcn_global_load_lds((const unsigned*)((const char*)(gbase) + (voff)[_i]), (LAS unsigned*)(lds + (bufoff) + ldsw + _i * 8192), 16, 0, 0); } while (0)
; #define PG8_LDA(dst, b, h) do { _Pragma("unroll") for (int m = 0; m < 4; ++m) _Pragma("unroll") for (int k = 0; k < 2; ++k) dst[m][k] = *(const LAS bf16x8*)(lds + PG8_SA(b, h) + aoff + m * 2048 + k * 1024); } while (0)
; #define PG8_LDB(dst, b, h) do { _Pragma("unroll") for (int n = 0; n < 2; ++n) _Pragma("unroll") for (int k = 0; k < 2; ++k) dst[n][k] = *(const LAS bf16x8*)(lds + PG8_SB(b, h) + boff + n * 2048 + k * 1024); } while (0)
; #define PG8_MMA(ai, bj, At, Bt) do { __builtin_amdgcn_s_setprio(1); _Pragma("unroll") for (int m = 0; m < 4; ++m) _Pragma("unroll") for (int n = 0; n < 2; ++n) _Pragma("unroll") for (int k = 0; k < 2; ++k) \
;         acc[ai][bj][m][n] = __builtin_amdgcn_mfma_f32_16x16x32_bf16(Bt[n][k], At[m][k], acc[ai][bj][m][n], 0, 0, 0); __builtin_amdgcn_s_setprio(0); } while (0)
; #define PG8_WAIT_V(n) asm volatile("s_waitcnt vmcnt(" #n ")" ::: "memory")
; #define PG8_WAIT_L(n) asm volatile("s_waitcnt lgkmcnt(" #n ")" ::: "memory")
; #define PG8_BAR __builtin_amdgcn_s_barrier()
; #define PG8_SCHED __builtin_amdgcn_sched_barrier(0)
; template <class Epi, class Sched>
; __device__ __forceinline__ void gemm_phase(LAS unsigned char* lds, const int K, const Sched& S, const Epi& E) {
;     ...
;             const char* a1 = cA + (size_t)(t + 1) * kstep;
;             const char* a2 = last ? nA : cA + (size_t)(t + 2) * kstep; const char* b2 = last ? nB : cB + (size_t)(t + 2) * kstep;
;             const char* a3 = a2 + kstep; const char* b3 = b2 + kstep;
;             PG8_LDB(B0, 0, 0); PG8_LDB(B1, 0, 1); PG8_SCHED; PG8_LDA(At, 0, 0); PG8_STAGE(PG8_SA(1, 1), a1 + hstep, voffA);
;             PG8_WAIT_V(8); PG8_WAIT_L(0); PG8_BAR; PG8_MMA(0, 0, At, B0); PG8_MMA(0, 1, At, B1); PG8_BAR; PG8_SCHED;
;             PG8_LDA(At, 0, 1); PG8_STAGE(PG8_SB(0, 0), b2, voffB); PG8_STAGE(PG8_SB(0, 1), b2 + hstep, voffB); PG8_STAGE(PG8_SA(0, 0), a2, voffA);
;             PG8_WAIT_V(8); PG8_WAIT_L(0); PG8_BAR; PG8_MMA(1, 0, At, B0); PG8_MMA(1, 1, At, B1); PG8_BAR; PG8_SCHED;
.LBB0_1433:
	ds_read_b128 v[140:143], v151
	ds_read_b128 v[144:147], v151 offset:1024
	ds_read_b128 v[156:159], v151 offset:2048
	ds_read_b128 v[160:163], v151 offset:3072
	ds_read_b128 v[164:167], v152
	ds_read_b128 v[168:171], v152 offset:1024
	ds_read_b128 v[172:175], v152 offset:2048
	ds_read_b128 v[176:179], v152 offset:3072
	s_add_u32 s25, s34, 0xfff80080
	s_addc_u32 s36, s35, -1
	s_cmp_eq_u32 s23, 28
	s_cselect_b32 s39, s27, s36
	s_cselect_b32 s38, s26, s25
	s_cselect_b32 s37, s31, s9
	s_cselect_b32 s36, s30, s8
	v_lshl_add_u64 v[212:213], s[34:35], 0, v[136:137]
	s_add_i32 m0, s42, 0xc000
	ds_read_b128 v[180:183], v153
	ds_read_b128 v[184:187], v153 offset:1024
	ds_read_b128 v[188:191], v153 offset:2048
	ds_read_b128 v[192:195], v153 offset:3072
	ds_read_b128 v[196:199], v153 offset:4096
	ds_read_b128 v[200:203], v153 offset:5120
	ds_read_b128 v[204:207], v153 offset:6144
	ds_read_b128 v[208:211], v153 offset:7168
	global_load_lds_dwordx4 v[212:213], off
	v_lshl_add_u64 v[212:213], s[34:35], 0, v[138:139]
	s_add_i32 m0, s42, 0xe000
	s_nop 0
	global_load_lds_dwordx4 v[212:213], off
	s_waitcnt vmcnt(8)
	s_waitcnt lgkmcnt(0)
	s_setprio 1
	s_barrier
	v_mfma_f32_16x16x32_bf16 v[124:127], v[140:143], v[180:183], v[124:127]
	v_mfma_f32_16x16x32_bf16 v[120:123], v[156:159], v[180:183], v[120:123]
	v_mfma_f32_16x16x32_bf16 v[108:111], v[140:143], v[188:191], v[108:111]
	v_mfma_f32_16x16x32_bf16 v[104:107], v[156:159], v[188:191], v[104:107]
	v_mfma_f32_16x16x32_bf16 v[92:95], v[140:143], v[196:199], v[92:95]
	v_mfma_f32_16x16x32_bf16 v[88:91], v[156:159], v[196:199], v[88:91]
	v_mfma_f32_16x16x32_bf16 v[76:79], v[140:143], v[204:207], v[76:79]
	v_mfma_f32_16x16x32_bf16 v[72:75], v[156:159], v[204:207], v[72:75]
	v_mfma_f32_16x16x32_bf16 v[124:127], v[144:147], v[184:187], v[124:127]
	v_mfma_f32_16x16x32_bf16 v[120:123], v[160:163], v[184:187], v[120:123]
	v_mfma_f32_16x16x32_bf16 v[108:111], v[144:147], v[192:195], v[108:111]
	v_mfma_f32_16x16x32_bf16 v[104:107], v[160:163], v[192:195], v[104:107]
	v_mfma_f32_16x16x32_bf16 v[92:95], v[144:147], v[200:203], v[92:95]
	v_mfma_f32_16x16x32_bf16 v[88:91], v[160:163], v[200:203], v[88:91]
	v_mfma_f32_16x16x32_bf16 v[76:79], v[144:147], v[208:211], v[76:79]
	v_mfma_f32_16x16x32_bf16 v[72:75], v[160:163], v[208:211], v[72:75]
	v_mfma_f32_16x16x32_bf16 v[116:119], v[164:167], v[180:183], v[116:119]
	v_mfma_f32_16x16x32_bf16 v[112:115], v[172:175], v[180:183], v[112:115]
	v_mfma_f32_16x16x32_bf16 v[100:103], v[164:167], v[188:191], v[100:103]
	v_mfma_f32_16x16x32_bf16 v[96:99], v[172:175], v[188:191], v[96:99]
	v_mfma_f32_16x16x32_bf16 v[84:87], v[164:167], v[196:199], v[84:87]
	v_mfma_f32_16x16x32_bf16 v[80:83], v[172:175], v[196:199], v[80:83]
	v_mfma_f32_16x16x32_bf16 v[68:71], v[164:167], v[204:207], v[68:71]
	v_mfma_f32_16x16x32_bf16 v[64:67], v[172:175], v[204:207], v[64:67]
	v_mfma_f32_16x16x32_bf16 v[116:119], v[168:171], v[184:187], v[116:119]
	v_mfma_f32_16x16x32_bf16 v[112:115], v[176:179], v[184:187], v[112:115]
	v_mfma_f32_16x16x32_bf16 v[100:103], v[168:171], v[192:195], v[100:103]
	v_mfma_f32_16x16x32_bf16 v[96:99], v[176:179], v[192:195], v[96:99]
	v_mfma_f32_16x16x32_bf16 v[84:87], v[168:171], v[200:203], v[84:87]
	v_mfma_f32_16x16x32_bf16 v[80:83], v[176:179], v[200:203], v[80:83]
	v_mfma_f32_16x16x32_bf16 v[68:71], v[168:171], v[208:211], v[68:71]
	v_mfma_f32_16x16x32_bf16 v[64:67], v[176:179], v[208:211], v[64:67]
	s_setprio 0
	s_barrier
	s_add_i32 s25, s49, s40
	v_lshl_add_u64 v[212:213], s[36:37], 0, v[132:133]
	s_mov_b32 m0, s25
	ds_read_b128 v[180:183], v153 offset:16384
	ds_read_b128 v[184:187], v153 offset:17408
	ds_read_b128 v[188:191], v153 offset:18432
	ds_read_b128 v[192:195], v153 offset:19456
	ds_read_b128 v[196:199], v153 offset:20480
	ds_read_b128 v[200:203], v153 offset:21504
	ds_read_b128 v[204:207], v153 offset:22528
	ds_read_b128 v[208:211], v153 offset:23552
	global_load_lds_dwordx4 v[212:213], off
	s_add_i32 m0, s25, 0x2000
	s_add_u32 s62, s36, 0x80000
	v_lshl_add_u64 v[214:215], s[36:37], 0, v[128:129]
	s_addc_u32 s63, s37, 0
	s_add_i32 s25, s50, s40
	global_load_lds_dwordx4 v[214:215], off
	v_lshl_add_u64 v[216:217], s[62:63], 0, v[132:133]
	s_mov_b32 m0, s25
	v_lshl_add_u64 v[218:219], s[38:39], 0, v[130:131]
	global_load_lds_dwordx4 v[216:217], off
	v_lshl_add_u64 v[216:217], s[62:63], 0, v[128:129]
	s_add_i32 m0, s25, 0x2000
	s_nop 0
	global_load_lds_dwordx4 v[216:217], off
	v_lshl_add_u64 v[216:217], s[38:39], 0, v[134:135]
	s_mov_b32 m0, s42
	s_nop 0
	global_load_lds_dwordx4 v[216:217], off
	s_mov_b32 m0, s43
	s_nop 0
	global_load_lds_dwordx4 v[218:219], off
	s_waitcnt vmcnt(8)
	s_waitcnt lgkmcnt(0)
	s_setprio 1
	s_barrier
; #define PG8_STAGE(bufoff, gbase, voff) do { _Pragma("unroll") for (int _i = 0; _i < 2; ++_i) \
;         __builtin_amdgcn_global_load_lds((const unsigned*)((const char*)(gbase) + (voff)[_i]), (LAS unsigned*)(lds + (bufoff) + ldsw + _i * 8192), 16, 0, 0); } while (0)
; #define PG8_LDA(dst, b, h) do { _Pragma("unroll") for (int m = 0; m < 4; ++m) _Pragma("unroll") for (int k = 0; k < 2; ++k) dst[m][k] = *(const LAS bf16x8*)(lds + PG8_SA(b, h) + aoff + m * 2048 + k * 1024); } while (0)
; #define PG8_LDB(dst, b, h) do { _Pragma("unroll") for (int n = 0; n < 2; ++n) _Pragma("unroll") for (int k = 0; k < 2; ++k) dst[n][k] = *(const LAS bf16x8*)(lds + PG8_SB(b, h) + boff + n * 2048 + k * 1024); } while (0)
; #define PG8_MMA(ai, bj, At, Bt) do { __builtin_amdgcn_s_setprio(1); _Pragma("unroll") for (int m = 0; m < 4; ++m) _Pragma("unroll") for (int n = 0; n < 2; ++n) _Pragma("unroll") for (int k = 0; k < 2; ++k) \
;         acc[ai][bj][m][n] = __builtin_amdgcn_mfma_f32_16x16x32_bf16(Bt[n][k], At[m][k], acc[ai][bj][m][n], 0, 0, 0); __builtin_amdgcn_s_setprio(0); } while (0)
; #define PG8_WAIT_V(n) asm volatile("s_waitcnt vmcnt(" #n ")" ::: "memory")
; #define PG8_WAIT_L(n) asm volatile("s_waitcnt lgkmcnt(" #n ")" ::: "memory")
; #define PG8_BAR __builtin_amdgcn_s_barrier()
; #define PG8_SCHED __builtin_amdgcn_sched_barrier(0)
; template <class Epi, class Sched>
; __device__ __forceinline__ void gemm_phase(LAS unsigned char* lds, const int K, const Sched& S, const Epi& E) {
;     ...
;             PG8_WAIT_V(8); PG8_WAIT_L(0); PG8_BAR; PG8_MMA(1, 0, At, B0); PG8_MMA(1, 1, At, B1); PG8_BAR; PG8_SCHED;
;             PG8_LDB(B0, 1, 0); PG8_LDB(B1, 1, 1); PG8_SCHED; PG8_LDA(At, 1, 0); PG8_STAGE(PG8_SA(0, 1), a2 + hstep, voffA);
;             PG8_WAIT_V(8); PG8_WAIT_L(0); PG8_BAR; PG8_MMA(0, 0, At, B0); PG8_MMA(0, 1, At, B1); PG8_BAR; PG8_SCHED;
	v_mfma_f32_16x16x32_bf16 v[60:63], v[140:143], v[180:183], v[60:63]
	v_mfma_f32_16x16x32_bf16 v[56:59], v[156:159], v[180:183], v[56:59]
	v_mfma_f32_16x16x32_bf16 v[44:47], v[140:143], v[188:191], v[44:47]
	v_mfma_f32_16x16x32_bf16 v[40:43], v[156:159], v[188:191], v[40:43]
	v_mfma_f32_16x16x32_bf16 v[28:31], v[140:143], v[196:199], v[28:31]
	v_mfma_f32_16x16x32_bf16 v[24:27], v[156:159], v[196:199], v[24:27]
	v_mfma_f32_16x16x32_bf16 v[12:15], v[140:143], v[204:207], v[12:15]
	v_mfma_f32_16x16x32_bf16 v[8:11], v[156:159], v[204:207], v[8:11]
	v_mfma_f32_16x16x32_bf16 v[60:63], v[144:147], v[184:187], v[60:63]
	v_mfma_f32_16x16x32_bf16 v[56:59], v[160:163], v[184:187], v[56:59]
	v_mfma_f32_16x16x32_bf16 v[44:47], v[144:147], v[192:195], v[44:47]
	v_mfma_f32_16x16x32_bf16 v[40:43], v[160:163], v[192:195], v[40:43]
	v_mfma_f32_16x16x32_bf16 v[28:31], v[144:147], v[200:203], v[28:31]
	v_mfma_f32_16x16x32_bf16 v[24:27], v[160:163], v[200:203], v[24:27]
	v_mfma_f32_16x16x32_bf16 v[12:15], v[144:147], v[208:211], v[12:15]
	v_mfma_f32_16x16x32_bf16 v[8:11], v[160:163], v[208:211], v[8:11]
	v_mfma_f32_16x16x32_bf16 v[52:55], v[164:167], v[180:183], v[52:55]
	v_mfma_f32_16x16x32_bf16 v[48:51], v[172:175], v[180:183], v[48:51]
	v_mfma_f32_16x16x32_bf16 v[36:39], v[164:167], v[188:191], v[36:39]
	v_mfma_f32_16x16x32_bf16 v[32:35], v[172:175], v[188:191], v[32:35]
	v_mfma_f32_16x16x32_bf16 v[20:23], v[164:167], v[196:199], v[20:23]
	v_mfma_f32_16x16x32_bf16 v[16:19], v[172:175], v[196:199], v[16:19]
	v_mfma_f32_16x16x32_bf16 v[4:7], v[164:167], v[204:207], v[4:7]
	v_mfma_f32_16x16x32_bf16 v[0:3], v[172:175], v[204:207], v[0:3]
	v_mfma_f32_16x16x32_bf16 v[52:55], v[168:171], v[184:187], v[52:55]
	v_mfma_f32_16x16x32_bf16 v[48:51], v[176:179], v[184:187], v[48:51]
	v_mfma_f32_16x16x32_bf16 v[36:39], v[168:171], v[192:195], v[36:39]
	v_mfma_f32_16x16x32_bf16 v[32:35], v[176:179], v[192:195], v[32:35]
	v_mfma_f32_16x16x32_bf16 v[20:23], v[168:171], v[200:203], v[20:23]
	v_mfma_f32_16x16x32_bf16 v[16:19], v[176:179], v[200:203], v[16:19]
	v_mfma_f32_16x16x32_bf16 v[4:7], v[168:171], v[208:211], v[4:7]
	v_mfma_f32_16x16x32_bf16 v[0:3], v[176:179], v[208:211], v[0:3]
	s_setprio 0
	s_barrier
	s_add_i32 s25, 0, 0x18000
	v_add_u32_e32 v155, s25, v149
	s_add_i32 s61, 0, 0x1c000
	ds_read_b128 v[140:143], v155
	ds_read_b128 v[144:147], v155 offset:1024
	ds_read_b128 v[156:159], v155 offset:2048
	ds_read_b128 v[160:163], v155 offset:3072
	v_add_u32_e32 v155, s61, v149
	ds_read_b128 v[164:167], v155
	ds_read_b128 v[168:171], v155 offset:1024
	ds_read_b128 v[172:175], v155 offset:2048
	ds_read_b128 v[176:179], v155 offset:3072
	s_add_u32 s38, s38, 0x80000
	s_addc_u32 s39, s39, 0
	s_mov_b32 m0, s44
	v_lshl_add_u64 v[220:221], s[38:39], 0, v[134:135]
	ds_read_b128 v[180:183], v153 offset:32768
	ds_read_b128 v[184:187], v153 offset:33792
	ds_read_b128 v[188:191], v153 offset:34816
	ds_read_b128 v[192:195], v153 offset:35840
	ds_read_b128 v[196:199], v153 offset:36864
	ds_read_b128 v[200:203], v153 offset:37888
	ds_read_b128 v[204:207], v153 offset:38912
	ds_read_b128 v[208:211], v153 offset:39936
	global_load_lds_dwordx4 v[220:221], off
	v_lshl_add_u64 v[220:221], s[38:39], 0, v[130:131]
	s_mov_b32 m0, s45
	s_nop 0
	global_load_lds_dwordx4 v[220:221], off
	s_waitcnt vmcnt(8)
	s_waitcnt lgkmcnt(0)
	s_setprio 1
	s_barrier
	v_mfma_f32_16x16x32_bf16 v[124:127], v[140:143], v[180:183], v[124:127]
	v_mfma_f32_16x16x32_bf16 v[120:123], v[156:159], v[180:183], v[120:123]
	v_mfma_f32_16x16x32_bf16 v[108:111], v[140:143], v[188:191], v[108:111]
	v_mfma_f32_16x16x32_bf16 v[104:107], v[156:159], v[188:191], v[104:107]
	v_mfma_f32_16x16x32_bf16 v[92:95], v[140:143], v[196:199], v[92:95]
	v_mfma_f32_16x16x32_bf16 v[88:91], v[156:159], v[196:199], v[88:91]
	v_mfma_f32_16x16x32_bf16 v[76:79], v[140:143], v[204:207], v[76:79]
	v_mfma_f32_16x16x32_bf16 v[72:75], v[156:159], v[204:207], v[72:75]
	v_mfma_f32_16x16x32_bf16 v[124:127], v[144:147], v[184:187], v[124:127]
	v_mfma_f32_16x16x32_bf16 v[120:123], v[160:163], v[184:187], v[120:123]
	v_mfma_f32_16x16x32_bf16 v[108:111], v[144:147], v[192:195], v[108:111]
	v_mfma_f32_16x16x32_bf16 v[104:107], v[160:163], v[192:195], v[104:107]
	v_mfma_f32_16x16x32_bf16 v[92:95], v[144:147], v[200:203], v[92:95]
	v_mfma_f32_16x16x32_bf16 v[88:91], v[160:163], v[200:203], v[88:91]
	v_mfma_f32_16x16x32_bf16 v[76:79], v[144:147], v[208:211], v[76:79]
	v_mfma_f32_16x16x32_bf16 v[72:75], v[160:163], v[208:211], v[72:75]
	v_mfma_f32_16x16x32_bf16 v[116:119], v[164:167], v[180:183], v[116:119]
	v_mfma_f32_16x16x32_bf16 v[112:115], v[172:175], v[180:183], v[112:115]
	v_mfma_f32_16x16x32_bf16 v[100:103], v[164:167], v[188:191], v[100:103]
	v_mfma_f32_16x16x32_bf16 v[96:99], v[172:175], v[188:191], v[96:99]
	v_mfma_f32_16x16x32_bf16 v[84:87], v[164:167], v[196:199], v[84:87]
	v_mfma_f32_16x16x32_bf16 v[80:83], v[172:175], v[196:199], v[80:83]
	v_mfma_f32_16x16x32_bf16 v[68:71], v[164:167], v[204:207], v[68:71]
	v_mfma_f32_16x16x32_bf16 v[64:67], v[172:175], v[204:207], v[64:67]
	v_mfma_f32_16x16x32_bf16 v[116:119], v[168:171], v[184:187], v[116:119]
	v_mfma_f32_16x16x32_bf16 v[112:115], v[176:179], v[184:187], v[112:115]
	v_mfma_f32_16x16x32_bf16 v[100:103], v[168:171], v[192:195], v[100:103]
	v_mfma_f32_16x16x32_bf16 v[96:99], v[176:179], v[192:195], v[96:99]
	v_mfma_f32_16x16x32_bf16 v[84:87], v[168:171], v[200:203], v[84:87]
	v_mfma_f32_16x16x32_bf16 v[80:83], v[176:179], v[200:203], v[80:83]
	v_mfma_f32_16x16x32_bf16 v[68:71], v[168:171], v[208:211], v[68:71]
	v_mfma_f32_16x16x32_bf16 v[64:67], v[176:179], v[208:211], v[64:67]
	s_setprio 0
	s_barrier
; #define PG8_STAGE(bufoff, gbase, voff) do { _Pragma("unroll") for (int _i = 0; _i < 2; ++_i) \
;         __builtin_amdgcn_global_load_lds((const unsigned*)((const char*)(gbase) + (voff)[_i]), (LAS unsigned*)(lds + (bufoff) + ldsw + _i * 8192), 16, 0, 0); } while (0)
; #define PG8_LDA(dst, b, h) do { _Pragma("unroll") for (int m = 0; m < 4; ++m) _Pragma("unroll") for (int k = 0; k < 2; ++k) dst[m][k] = *(const LAS bf16x8*)(lds + PG8_SA(b, h) + aoff + m * 2048 + k * 1024); } while (0)
; #define PG8_MMA(ai, bj, At, Bt) do { __builtin_amdgcn_s_setprio(1); _Pragma("unroll") for (int m = 0; m < 4; ++m) _Pragma("unroll") for (int n = 0; n < 2; ++n) _Pragma("unroll") for (int k = 0; k < 2; ++k) \
;         acc[ai][bj][m][n] = __builtin_amdgcn_mfma_f32_16x16x32_bf16(Bt[n][k], At[m][k], acc[ai][bj][m][n], 0, 0, 0); __builtin_amdgcn_s_setprio(0); } while (0)
; #define PG8_WAIT_V(n) asm volatile("s_waitcnt vmcnt(" #n ")" ::: "memory")
; #define PG8_WAIT_L(n) asm volatile("s_waitcnt lgkmcnt(" #n ")" ::: "memory")
; #define PG8_BAR __builtin_amdgcn_s_barrier()
; #define PG8_SCHED __builtin_amdgcn_sched_barrier(0)
; template <class Epi, class Sched>
; __device__ __forceinline__ void gemm_phase(LAS unsigned char* lds, const int K, const Sched& S, const Epi& E) {
;     ...
;             PG8_LDA(At, 1, 1); PG8_STAGE(PG8_SB(1, 0), b3, voffB); PG8_STAGE(PG8_SB(1, 1), b3 + hstep, voffB); PG8_STAGE(PG8_SA(1, 0), a3, voffA);
;             PG8_WAIT_V(8); PG8_WAIT_L(0); PG8_BAR; PG8_MMA(1, 0, At, B0); PG8_MMA(1, 1, At, B1); PG8_BAR; PG8_SCHED;
;         }
;         if (wr == 0) PG8_BAR;
	s_add_i32 s25, s25, s40
	v_lshl_add_u64 v[212:213], v[212:213], 0, s[16:17]
	s_mov_b32 m0, s25
	ds_read_b128 v[180:183], v153 offset:49152
	ds_read_b128 v[184:187], v153 offset:50176
	ds_read_b128 v[188:191], v153 offset:51200
	ds_read_b128 v[192:195], v153 offset:52224
	ds_read_b128 v[196:199], v153 offset:53248
	ds_read_b128 v[200:203], v153 offset:54272
	ds_read_b128 v[204:207], v153 offset:55296
	ds_read_b128 v[208:211], v153 offset:56320
	global_load_lds_dwordx4 v[212:213], off
	s_add_i32 m0, s25, 0x2000
	s_add_u32 s36, s36, 0x80080
	v_lshl_add_u64 v[212:213], v[214:215], 0, s[16:17]
	s_addc_u32 s37, s37, 0
	s_add_i32 s25, s61, s40
	global_load_lds_dwordx4 v[212:213], off
	v_lshl_add_u64 v[212:213], s[36:37], 0, v[132:133]
	s_mov_b32 m0, s25
	s_nop 0
	global_load_lds_dwordx4 v[212:213], off
	v_lshl_add_u64 v[212:213], s[36:37], 0, v[128:129]
	s_add_i32 m0, s25, 0x2000
	s_nop 0
	global_load_lds_dwordx4 v[212:213], off
	v_lshl_add_u64 v[212:213], v[216:217], 0, s[16:17]
	s_mov_b32 m0, s47
	s_nop 0
	global_load_lds_dwordx4 v[212:213], off
	v_lshl_add_u64 v[212:213], v[218:219], 0, s[16:17]
	s_mov_b32 m0, s48
	s_nop 0
	global_load_lds_dwordx4 v[212:213], off
	s_waitcnt vmcnt(8)
	s_waitcnt lgkmcnt(0)
	s_setprio 1
	s_barrier
	v_mfma_f32_16x16x32_bf16 v[60:63], v[140:143], v[180:183], v[60:63]
	v_mfma_f32_16x16x32_bf16 v[56:59], v[156:159], v[180:183], v[56:59]
	v_mfma_f32_16x16x32_bf16 v[44:47], v[140:143], v[188:191], v[44:47]
	v_mfma_f32_16x16x32_bf16 v[40:43], v[156:159], v[188:191], v[40:43]
	v_mfma_f32_16x16x32_bf16 v[28:31], v[140:143], v[196:199], v[28:31]
	v_mfma_f32_16x16x32_bf16 v[24:27], v[156:159], v[196:199], v[24:27]
	v_mfma_f32_16x16x32_bf16 v[12:15], v[140:143], v[204:207], v[12:15]
	v_mfma_f32_16x16x32_bf16 v[8:11], v[156:159], v[204:207], v[8:11]
	v_mfma_f32_16x16x32_bf16 v[60:63], v[144:147], v[184:187], v[60:63]
	v_mfma_f32_16x16x32_bf16 v[56:59], v[160:163], v[184:187], v[56:59]
	v_mfma_f32_16x16x32_bf16 v[44:47], v[144:147], v[192:195], v[44:47]
	v_mfma_f32_16x16x32_bf16 v[40:43], v[160:163], v[192:195], v[40:43]
	v_mfma_f32_16x16x32_bf16 v[28:31], v[144:147], v[200:203], v[28:31]
	v_mfma_f32_16x16x32_bf16 v[24:27], v[160:163], v[200:203], v[24:27]
	v_mfma_f32_16x16x32_bf16 v[12:15], v[144:147], v[208:211], v[12:15]
	v_mfma_f32_16x16x32_bf16 v[8:11], v[160:163], v[208:211], v[8:11]
	v_mfma_f32_16x16x32_bf16 v[52:55], v[164:167], v[180:183], v[52:55]
	v_mfma_f32_16x16x32_bf16 v[48:51], v[172:175], v[180:183], v[48:51]
	v_mfma_f32_16x16x32_bf16 v[36:39], v[164:167], v[188:191], v[36:39]
	v_mfma_f32_16x16x32_bf16 v[32:35], v[172:175], v[188:191], v[32:35]
	v_mfma_f32_16x16x32_bf16 v[20:23], v[164:167], v[196:199], v[20:23]
	v_mfma_f32_16x16x32_bf16 v[16:19], v[172:175], v[196:199], v[16:19]
	v_mfma_f32_16x16x32_bf16 v[4:7], v[164:167], v[204:207], v[4:7]
	v_mfma_f32_16x16x32_bf16 v[0:3], v[172:175], v[204:207], v[0:3]
	v_mfma_f32_16x16x32_bf16 v[52:55], v[168:171], v[184:187], v[52:55]
	v_mfma_f32_16x16x32_bf16 v[48:51], v[176:179], v[184:187], v[48:51]
	v_mfma_f32_16x16x32_bf16 v[36:39], v[168:171], v[192:195], v[36:39]
	v_mfma_f32_16x16x32_bf16 v[32:35], v[176:179], v[192:195], v[32:35]
	v_mfma_f32_16x16x32_bf16 v[20:23], v[168:171], v[200:203], v[20:23]
	v_mfma_f32_16x16x32_bf16 v[16:19], v[176:179], v[200:203], v[16:19]
	v_mfma_f32_16x16x32_bf16 v[4:7], v[168:171], v[208:211], v[4:7]
	v_mfma_f32_16x16x32_bf16 v[0:3], v[176:179], v[208:211], v[0:3]
	s_setprio 0
	s_barrier
	s_add_i32 s23, s23, 2
	s_add_u32 s34, s34, 0x100
	s_addc_u32 s35, s35, 0
	s_add_u32 s8, s8, 0x100
	s_addc_u32 s9, s9, 0
	s_cmp_gt_u32 s23, 29
	s_cbranch_scc0 .LBB0_1433
	s_and_b64 vcc, exec, s[18:19]
	s_cbranch_vccz .LBB0_1436
	s_barrier

; #define PG8_STAGE(bufoff, gbase, voff) do { _Pragma("unroll") for (int _i = 0; _i < 2; ++_i) \
;         __builtin_amdgcn_global_load_lds((const unsigned*)((const char*)(gbase) + (voff)[_i]), (LAS unsigned*)(lds + (bufoff) + ldsw + _i * 8192), 16, 0, 0); } while (0)
; #define PG8_LDA(dst, b, h) do { _Pragma("unroll") for (int m = 0; m < 4; ++m) _Pragma("unroll") for (int k = 0; k < 2; ++k) dst[m][k] = *(const LAS bf16x8*)(lds + PG8_SA(b, h) + aoff + m * 2048 + k * 1024); } while (0)
; #define PG8_LDB(dst, b, h) do { _Pragma("unroll") for (int n = 0; n < 2; ++n) _Pragma("unroll") for (int k = 0; k < 2; ++k) dst[n][k] = *(const LAS bf16x8*)(lds + PG8_SB(b, h) + boff + n * 2048 + k * 1024); } while (0)
; #define PG8_MMA(ai, bj, At, Bt) do { __builtin_amdgcn_s_setprio(1); _Pragma("unroll") for (int m = 0; m < 4; ++m) _Pragma("unroll") for (int n = 0; n < 2; ++n) _Pragma("unroll") for (int k = 0; k < 2; ++k) \
;         acc[ai][bj][m][n] = __builtin_amdgcn_mfma_f32_16x16x32_bf16(Bt[n][k], At[m][k], acc[ai][bj][m][n], 0, 0, 0); __builtin_amdgcn_s_setprio(0); } while (0)
; #define PG8_WAIT_V(n) asm volatile("s_waitcnt vmcnt(" #n ")" ::: "memory")
; #define PG8_WAIT_L(n) asm volatile("s_waitcnt lgkmcnt(" #n ")" ::: "memory")
; #define PG8_BAR __builtin_amdgcn_s_barrier()
; #define PG8_SCHED __builtin_amdgcn_sched_barrier(0)
; template <class Epi, class Sched>
; __device__ __forceinline__ void gemm_phase(LAS unsigned char* lds, const int K, const Sched& S, const Epi& E) {
;     ...
;             const char* a1 = cA + (size_t)(t + 1) * kstep;
;             const char* a2 = last ? nA : cA + (size_t)(t + 2) * kstep; const char* b2 = last ? nB : cB + (size_t)(t + 2) * kstep;
;             const char* a3 = a2 + kstep; const char* b3 = b2 + kstep;
;             PG8_LDB(B0, 0, 0); PG8_LDB(B1, 0, 1); PG8_SCHED; PG8_LDA(At, 0, 0); PG8_STAGE(PG8_SA(1, 1), a1 + hstep, voffA);
;             PG8_WAIT_V(8); PG8_WAIT_L(0); PG8_BAR; PG8_MMA(0, 0, At, B0); PG8_MMA(0, 1, At, B1); PG8_BAR; PG8_SCHED;
;             PG8_LDA(At, 0, 1); PG8_STAGE(PG8_SB(0, 0), b2, voffB); PG8_STAGE(PG8_SB(0, 1), b2 + hstep, voffB); PG8_STAGE(PG8_SA(0, 0), a2, voffA);
;             PG8_WAIT_V(8); PG8_WAIT_L(0); PG8_BAR; PG8_MMA(1, 0, At, B0); PG8_MMA(1, 1, At, B1); PG8_BAR; PG8_SCHED;
.LBB0_1513:
	ds_read_b128 v[140:143], v147
	ds_read_b128 v[152:155], v147 offset:1024
	ds_read_b128 v[156:159], v147 offset:2048
	ds_read_b128 v[160:163], v147 offset:3072
	ds_read_b128 v[164:167], v148
	ds_read_b128 v[168:171], v148 offset:1024
	ds_read_b128 v[172:175], v148 offset:2048
	ds_read_b128 v[176:179], v148 offset:3072
	s_add_u32 s24, s22, 0xffea0080
	s_addc_u32 s25, s23, -1
	s_cmpk_eq_i32 s61, 0x54
	s_cselect_b32 s27, s17, s25
	s_cselect_b32 s26, s16, s24
	s_cselect_b32 s25, s19, s9
	s_cselect_b32 s24, s18, s8
	s_mov_b32 m0, s45
	v_lshl_add_u64 v[212:213], s[22:23], 0, v[136:137]
	ds_read_b128 v[180:183], v149
	ds_read_b128 v[184:187], v149 offset:1024
	ds_read_b128 v[188:191], v149 offset:2048
	ds_read_b128 v[192:195], v149 offset:3072
	ds_read_b128 v[196:199], v149 offset:4096
	ds_read_b128 v[200:203], v149 offset:5120
	ds_read_b128 v[204:207], v149 offset:6144
	ds_read_b128 v[208:211], v149 offset:7168
	global_load_lds_dwordx4 v[212:213], off
	v_lshl_add_u64 v[212:213], s[22:23], 0, v[138:139]
	s_mov_b32 m0, s46
	s_nop 0
	global_load_lds_dwordx4 v[212:213], off
	s_waitcnt vmcnt(8)
	s_waitcnt lgkmcnt(0)
	s_setprio 1
	s_barrier
	v_mfma_f32_16x16x32_bf16 v[124:127], v[140:143], v[180:183], v[124:127]
	v_mfma_f32_16x16x32_bf16 v[120:123], v[156:159], v[180:183], v[120:123]
	v_mfma_f32_16x16x32_bf16 v[108:111], v[140:143], v[188:191], v[108:111]
	v_mfma_f32_16x16x32_bf16 v[104:107], v[156:159], v[188:191], v[104:107]
	v_mfma_f32_16x16x32_bf16 v[92:95], v[140:143], v[196:199], v[92:95]
	v_mfma_f32_16x16x32_bf16 v[88:91], v[156:159], v[196:199], v[88:91]
	v_mfma_f32_16x16x32_bf16 v[76:79], v[140:143], v[204:207], v[76:79]
	v_mfma_f32_16x16x32_bf16 v[72:75], v[156:159], v[204:207], v[72:75]
	v_mfma_f32_16x16x32_bf16 v[124:127], v[152:155], v[184:187], v[124:127]
	v_mfma_f32_16x16x32_bf16 v[120:123], v[160:163], v[184:187], v[120:123]
	v_mfma_f32_16x16x32_bf16 v[108:111], v[152:155], v[192:195], v[108:111]
	v_mfma_f32_16x16x32_bf16 v[104:107], v[160:163], v[192:195], v[104:107]
	v_mfma_f32_16x16x32_bf16 v[92:95], v[152:155], v[200:203], v[92:95]
	v_mfma_f32_16x16x32_bf16 v[88:91], v[160:163], v[200:203], v[88:91]
	v_mfma_f32_16x16x32_bf16 v[76:79], v[152:155], v[208:211], v[76:79]
	v_mfma_f32_16x16x32_bf16 v[72:75], v[160:163], v[208:211], v[72:75]
	v_mfma_f32_16x16x32_bf16 v[116:119], v[164:167], v[180:183], v[116:119]
	v_mfma_f32_16x16x32_bf16 v[112:115], v[172:175], v[180:183], v[112:115]
	v_mfma_f32_16x16x32_bf16 v[100:103], v[164:167], v[188:191], v[100:103]
	v_mfma_f32_16x16x32_bf16 v[96:99], v[172:175], v[188:191], v[96:99]
	v_mfma_f32_16x16x32_bf16 v[84:87], v[164:167], v[196:199], v[84:87]
	v_mfma_f32_16x16x32_bf16 v[80:83], v[172:175], v[196:199], v[80:83]
	v_mfma_f32_16x16x32_bf16 v[68:71], v[164:167], v[204:207], v[68:71]
	v_mfma_f32_16x16x32_bf16 v[64:67], v[172:175], v[204:207], v[64:67]
	v_mfma_f32_16x16x32_bf16 v[116:119], v[168:171], v[184:187], v[116:119]
	v_mfma_f32_16x16x32_bf16 v[112:115], v[176:179], v[184:187], v[112:115]
	v_mfma_f32_16x16x32_bf16 v[100:103], v[168:171], v[192:195], v[100:103]
	v_mfma_f32_16x16x32_bf16 v[96:99], v[176:179], v[192:195], v[96:99]
	v_mfma_f32_16x16x32_bf16 v[84:87], v[168:171], v[200:203], v[84:87]
	v_mfma_f32_16x16x32_bf16 v[80:83], v[176:179], v[200:203], v[80:83]
	v_mfma_f32_16x16x32_bf16 v[68:71], v[168:171], v[208:211], v[68:71]
	v_mfma_f32_16x16x32_bf16 v[64:67], v[176:179], v[208:211], v[64:67]
	s_setprio 0
	s_barrier
	s_mov_b32 m0, s47
	v_lshl_add_u64 v[212:213], s[24:25], 0, v[130:131]
	s_add_u32 s62, s24, 0x160000
	ds_read_b128 v[180:183], v149 offset:16384
	ds_read_b128 v[184:187], v149 offset:17408
	ds_read_b128 v[188:191], v149 offset:18432
	ds_read_b128 v[192:195], v149 offset:19456
	ds_read_b128 v[196:199], v149 offset:20480
	ds_read_b128 v[200:203], v149 offset:21504
	ds_read_b128 v[204:207], v149 offset:22528
	ds_read_b128 v[208:211], v149 offset:23552
	global_load_lds_dwordx4 v[212:213], off
	v_lshl_add_u64 v[214:215], s[24:25], 0, v[134:135]
	s_mov_b32 m0, s48
	s_addc_u32 s63, s25, 0
	s_add_i32 s64, s44, s34
	global_load_lds_dwordx4 v[214:215], off
	v_lshl_add_u64 v[216:217], s[62:63], 0, v[130:131]
	s_mov_b32 m0, s64
	v_lshl_add_u64 v[218:219], s[26:27], 0, v[132:133]
	global_load_lds_dwordx4 v[216:217], off
	v_lshl_add_u64 v[216:217], s[62:63], 0, v[134:135]
	s_add_i32 m0, s64, 0x2000
	s_nop 0
	global_load_lds_dwordx4 v[216:217], off
	v_lshl_add_u64 v[216:217], s[26:27], 0, v[128:129]
	s_mov_b32 m0, s35
	s_nop 0
	global_load_lds_dwordx4 v[216:217], off
	s_mov_b32 m0, s36
	s_nop 0
	global_load_lds_dwordx4 v[218:219], off
	s_waitcnt vmcnt(8)
	s_waitcnt lgkmcnt(0)
	s_setprio 1
	s_barrier
; #define PG8_STAGE(bufoff, gbase, voff) do { _Pragma("unroll") for (int _i = 0; _i < 2; ++_i) \
;         __builtin_amdgcn_global_load_lds((const unsigned*)((const char*)(gbase) + (voff)[_i]), (LAS unsigned*)(lds + (bufoff) + ldsw + _i * 8192), 16, 0, 0); } while (0)
; #define PG8_LDA(dst, b, h) do { _Pragma("unroll") for (int m = 0; m < 4; ++m) _Pragma("unroll") for (int k = 0; k < 2; ++k) dst[m][k] = *(const LAS bf16x8*)(lds + PG8_SA(b, h) + aoff + m * 2048 + k * 1024); } while (0)
; #define PG8_LDB(dst, b, h) do { _Pragma("unroll") for (int n = 0; n < 2; ++n) _Pragma("unroll") for (int k = 0; k < 2; ++k) dst[n][k] = *(const LAS bf16x8*)(lds + PG8_SB(b, h) + boff + n * 2048 + k * 1024); } while (0)
; #define PG8_MMA(ai, bj, At, Bt) do { __builtin_amdgcn_s_setprio(1); _Pragma("unroll") for (int m = 0; m < 4; ++m) _Pragma("unroll") for (int n = 0; n < 2; ++n) _Pragma("unroll") for (int k = 0; k < 2; ++k) \
;         acc[ai][bj][m][n] = __builtin_amdgcn_mfma_f32_16x16x32_bf16(Bt[n][k], At[m][k], acc[ai][bj][m][n], 0, 0, 0); __builtin_amdgcn_s_setprio(0); } while (0)
; #define PG8_WAIT_V(n) asm volatile("s_waitcnt vmcnt(" #n ")" ::: "memory")
; #define PG8_WAIT_L(n) asm volatile("s_waitcnt lgkmcnt(" #n ")" ::: "memory")
; #define PG8_BAR __builtin_amdgcn_s_barrier()
; #define PG8_SCHED __builtin_amdgcn_sched_barrier(0)
; template <class Epi, class Sched>
; __device__ __forceinline__ void gemm_phase(LAS unsigned char* lds, const int K, const Sched& S, const Epi& E) {
;     ...
;             PG8_WAIT_V(8); PG8_WAIT_L(0); PG8_BAR; PG8_MMA(1, 0, At, B0); PG8_MMA(1, 1, At, B1); PG8_BAR; PG8_SCHED;
;             PG8_LDB(B0, 1, 0); PG8_LDB(B1, 1, 1); PG8_SCHED; PG8_LDA(At, 1, 0); PG8_STAGE(PG8_SA(0, 1), a2 + hstep, voffA);
;             PG8_WAIT_V(8); PG8_WAIT_L(0); PG8_BAR; PG8_MMA(0, 0, At, B0); PG8_MMA(0, 1, At, B1); PG8_BAR; PG8_SCHED;
	v_mfma_f32_16x16x32_bf16 v[60:63], v[140:143], v[180:183], v[60:63]
	v_mfma_f32_16x16x32_bf16 v[56:59], v[156:159], v[180:183], v[56:59]
	v_mfma_f32_16x16x32_bf16 v[44:47], v[140:143], v[188:191], v[44:47]
	v_mfma_f32_16x16x32_bf16 v[40:43], v[156:159], v[188:191], v[40:43]
	v_mfma_f32_16x16x32_bf16 v[28:31], v[140:143], v[196:199], v[28:31]
	v_mfma_f32_16x16x32_bf16 v[24:27], v[156:159], v[196:199], v[24:27]
	v_mfma_f32_16x16x32_bf16 v[12:15], v[140:143], v[204:207], v[12:15]
	v_mfma_f32_16x16x32_bf16 v[8:11], v[156:159], v[204:207], v[8:11]
	v_mfma_f32_16x16x32_bf16 v[60:63], v[152:155], v[184:187], v[60:63]
	v_mfma_f32_16x16x32_bf16 v[56:59], v[160:163], v[184:187], v[56:59]
	v_mfma_f32_16x16x32_bf16 v[44:47], v[152:155], v[192:195], v[44:47]
	v_mfma_f32_16x16x32_bf16 v[40:43], v[160:163], v[192:195], v[40:43]
	v_mfma_f32_16x16x32_bf16 v[28:31], v[152:155], v[200:203], v[28:31]
	v_mfma_f32_16x16x32_bf16 v[24:27], v[160:163], v[200:203], v[24:27]
	v_mfma_f32_16x16x32_bf16 v[12:15], v[152:155], v[208:211], v[12:15]
	v_mfma_f32_16x16x32_bf16 v[8:11], v[160:163], v[208:211], v[8:11]
	v_mfma_f32_16x16x32_bf16 v[52:55], v[164:167], v[180:183], v[52:55]
	v_mfma_f32_16x16x32_bf16 v[48:51], v[172:175], v[180:183], v[48:51]
	v_mfma_f32_16x16x32_bf16 v[36:39], v[164:167], v[188:191], v[36:39]
	v_mfma_f32_16x16x32_bf16 v[32:35], v[172:175], v[188:191], v[32:35]
	v_mfma_f32_16x16x32_bf16 v[20:23], v[164:167], v[196:199], v[20:23]
	v_mfma_f32_16x16x32_bf16 v[16:19], v[172:175], v[196:199], v[16:19]
	v_mfma_f32_16x16x32_bf16 v[4:7], v[164:167], v[204:207], v[4:7]
	v_mfma_f32_16x16x32_bf16 v[0:3], v[172:175], v[204:207], v[0:3]
	v_mfma_f32_16x16x32_bf16 v[52:55], v[168:171], v[184:187], v[52:55]
	v_mfma_f32_16x16x32_bf16 v[48:51], v[176:179], v[184:187], v[48:51]
	v_mfma_f32_16x16x32_bf16 v[36:39], v[168:171], v[192:195], v[36:39]
	v_mfma_f32_16x16x32_bf16 v[32:35], v[176:179], v[192:195], v[32:35]
	v_mfma_f32_16x16x32_bf16 v[20:23], v[168:171], v[200:203], v[20:23]
	v_mfma_f32_16x16x32_bf16 v[16:19], v[176:179], v[200:203], v[16:19]
	v_mfma_f32_16x16x32_bf16 v[4:7], v[168:171], v[208:211], v[4:7]
	v_mfma_f32_16x16x32_bf16 v[0:3], v[176:179], v[208:211], v[0:3]
	s_setprio 0
	s_barrier
	s_add_i32 s62, 0, 0x18000
	v_add_u32_e32 v151, s62, v146
	s_add_i32 s63, 0, 0x1c000
	ds_read_b128 v[140:143], v151
	ds_read_b128 v[152:155], v151 offset:1024
	ds_read_b128 v[156:159], v151 offset:2048
	ds_read_b128 v[160:163], v151 offset:3072
	v_add_u32_e32 v151, s63, v146
	ds_read_b128 v[164:167], v151
	ds_read_b128 v[168:171], v151 offset:1024
	ds_read_b128 v[172:175], v151 offset:2048
	ds_read_b128 v[176:179], v151 offset:3072
	s_add_u32 s26, s26, 0x160000
	s_addc_u32 s27, s27, 0
	s_mov_b32 m0, s37
	v_lshl_add_u64 v[220:221], s[26:27], 0, v[128:129]
	ds_read_b128 v[180:183], v149 offset:32768
	ds_read_b128 v[184:187], v149 offset:33792
	ds_read_b128 v[188:191], v149 offset:34816
	ds_read_b128 v[192:195], v149 offset:35840
	ds_read_b128 v[196:199], v149 offset:36864
	ds_read_b128 v[200:203], v149 offset:37888
	ds_read_b128 v[204:207], v149 offset:38912
	ds_read_b128 v[208:211], v149 offset:39936
	global_load_lds_dwordx4 v[220:221], off
	v_lshl_add_u64 v[220:221], s[26:27], 0, v[132:133]
	s_mov_b32 m0, s38
	s_nop 0
	global_load_lds_dwordx4 v[220:221], off
	s_waitcnt vmcnt(8)
	s_waitcnt lgkmcnt(0)
	s_setprio 1
	s_barrier
	v_mfma_f32_16x16x32_bf16 v[124:127], v[140:143], v[180:183], v[124:127]
	v_mfma_f32_16x16x32_bf16 v[120:123], v[156:159], v[180:183], v[120:123]
	v_mfma_f32_16x16x32_bf16 v[108:111], v[140:143], v[188:191], v[108:111]
	v_mfma_f32_16x16x32_bf16 v[104:107], v[156:159], v[188:191], v[104:107]
	v_mfma_f32_16x16x32_bf16 v[92:95], v[140:143], v[196:199], v[92:95]
	v_mfma_f32_16x16x32_bf16 v[88:91], v[156:159], v[196:199], v[88:91]
	v_mfma_f32_16x16x32_bf16 v[76:79], v[140:143], v[204:207], v[76:79]
	v_mfma_f32_16x16x32_bf16 v[72:75], v[156:159], v[204:207], v[72:75]
	v_mfma_f32_16x16x32_bf16 v[124:127], v[152:155], v[184:187], v[124:127]
	v_mfma_f32_16x16x32_bf16 v[120:123], v[160:163], v[184:187], v[120:123]
	v_mfma_f32_16x16x32_bf16 v[108:111], v[152:155], v[192:195], v[108:111]
	v_mfma_f32_16x16x32_bf16 v[104:107], v[160:163], v[192:195], v[104:107]
	v_mfma_f32_16x16x32_bf16 v[92:95], v[152:155], v[200:203], v[92:95]
	v_mfma_f32_16x16x32_bf16 v[88:91], v[160:163], v[200:203], v[88:91]
	v_mfma_f32_16x16x32_bf16 v[76:79], v[152:155], v[208:211], v[76:79]
	v_mfma_f32_16x16x32_bf16 v[72:75], v[160:163], v[208:211], v[72:75]
	v_mfma_f32_16x16x32_bf16 v[116:119], v[164:167], v[180:183], v[116:119]
	v_mfma_f32_16x16x32_bf16 v[112:115], v[172:175], v[180:183], v[112:115]
	v_mfma_f32_16x16x32_bf16 v[100:103], v[164:167], v[188:191], v[100:103]
	v_mfma_f32_16x16x32_bf16 v[96:99], v[172:175], v[188:191], v[96:99]
	v_mfma_f32_16x16x32_bf16 v[84:87], v[164:167], v[196:199], v[84:87]
	v_mfma_f32_16x16x32_bf16 v[80:83], v[172:175], v[196:199], v[80:83]
	v_mfma_f32_16x16x32_bf16 v[68:71], v[164:167], v[204:207], v[68:71]
	v_mfma_f32_16x16x32_bf16 v[64:67], v[172:175], v[204:207], v[64:67]
	v_mfma_f32_16x16x32_bf16 v[116:119], v[168:171], v[184:187], v[116:119]
	v_mfma_f32_16x16x32_bf16 v[112:115], v[176:179], v[184:187], v[112:115]
	v_mfma_f32_16x16x32_bf16 v[100:103], v[168:171], v[192:195], v[100:103]
	v_mfma_f32_16x16x32_bf16 v[96:99], v[176:179], v[192:195], v[96:99]
	v_mfma_f32_16x16x32_bf16 v[84:87], v[168:171], v[200:203], v[84:87]
	v_mfma_f32_16x16x32_bf16 v[80:83], v[176:179], v[200:203], v[80:83]
	v_mfma_f32_16x16x32_bf16 v[68:71], v[168:171], v[208:211], v[68:71]
	v_mfma_f32_16x16x32_bf16 v[64:67], v[176:179], v[208:211], v[64:67]
	s_setprio 0
	s_barrier
; #define PG8_STAGE(bufoff, gbase, voff) do { _Pragma("unroll") for (int _i = 0; _i < 2; ++_i) \
;         __builtin_amdgcn_global_load_lds((const unsigned*)((const char*)(gbase) + (voff)[_i]), (LAS unsigned*)(lds + (bufoff) + ldsw + _i * 8192), 16, 0, 0); } while (0)
; #define PG8_LDA(dst, b, h) do { _Pragma("unroll") for (int m = 0; m < 4; ++m) _Pragma("unroll") for (int k = 0; k < 2; ++k) dst[m][k] = *(const LAS bf16x8*)(lds + PG8_SA(b, h) + aoff + m * 2048 + k * 1024); } while (0)
; #define PG8_MMA(ai, bj, At, Bt) do { __builtin_amdgcn_s_setprio(1); _Pragma("unroll") for (int m = 0; m < 4; ++m) _Pragma("unroll") for (int n = 0; n < 2; ++n) _Pragma("unroll") for (int k = 0; k < 2; ++k) \
;         acc[ai][bj][m][n] = __builtin_amdgcn_mfma_f32_16x16x32_bf16(Bt[n][k], At[m][k], acc[ai][bj][m][n], 0, 0, 0); __builtin_amdgcn_s_setprio(0); } while (0)
; #define PG8_WAIT_V(n) asm volatile("s_waitcnt vmcnt(" #n ")" ::: "memory")
; #define PG8_WAIT_L(n) asm volatile("s_waitcnt lgkmcnt(" #n ")" ::: "memory")
; #define PG8_BAR __builtin_amdgcn_s_barrier()
; #define PG8_SCHED __builtin_amdgcn_sched_barrier(0)
; template <class Epi, class Sched>
; __device__ __forceinline__ void gemm_phase(LAS unsigned char* lds, const int K, const Sched& S, const Epi& E) {
;     ...
;             PG8_LDA(At, 1, 1); PG8_STAGE(PG8_SB(1, 0), b3, voffB); PG8_STAGE(PG8_SB(1, 1), b3 + hstep, voffB); PG8_STAGE(PG8_SA(1, 0), a3, voffA);
;             PG8_WAIT_V(8); PG8_WAIT_L(0); PG8_BAR; PG8_MMA(1, 0, At, B0); PG8_MMA(1, 1, At, B1); PG8_BAR; PG8_SCHED;
;         }
;         if (wr == 0) PG8_BAR;
	s_add_i32 s26, s62, s34
	v_lshl_add_u64 v[212:213], v[212:213], 0, s[12:13]
	s_mov_b32 m0, s26
	ds_read_b128 v[180:183], v149 offset:49152
	ds_read_b128 v[184:187], v149 offset:50176
	ds_read_b128 v[188:191], v149 offset:51200
	ds_read_b128 v[192:195], v149 offset:52224
	ds_read_b128 v[196:199], v149 offset:53248
	ds_read_b128 v[200:203], v149 offset:54272
	ds_read_b128 v[204:207], v149 offset:55296
	ds_read_b128 v[208:211], v149 offset:56320
	global_load_lds_dwordx4 v[212:213], off
	s_add_i32 m0, s26, 0x2000
	s_add_u32 s24, s24, 0x160080
	v_lshl_add_u64 v[212:213], v[214:215], 0, s[12:13]
	s_addc_u32 s25, s25, 0
	s_add_i32 s26, s63, s34
	global_load_lds_dwordx4 v[212:213], off
	v_lshl_add_u64 v[212:213], s[24:25], 0, v[130:131]
	s_mov_b32 m0, s26
	s_nop 0
	global_load_lds_dwordx4 v[212:213], off
	v_lshl_add_u64 v[212:213], s[24:25], 0, v[134:135]
	s_add_i32 m0, s26, 0x2000
	s_nop 0
	global_load_lds_dwordx4 v[212:213], off
	v_lshl_add_u64 v[212:213], v[216:217], 0, s[12:13]
	s_mov_b32 m0, s42
	s_nop 0
	global_load_lds_dwordx4 v[212:213], off
	v_lshl_add_u64 v[212:213], v[218:219], 0, s[12:13]
	s_mov_b32 m0, s43
	s_nop 0
	global_load_lds_dwordx4 v[212:213], off
	s_waitcnt vmcnt(8)
	s_waitcnt lgkmcnt(0)
	s_setprio 1
	s_barrier
	v_mfma_f32_16x16x32_bf16 v[60:63], v[140:143], v[180:183], v[60:63]
	v_mfma_f32_16x16x32_bf16 v[56:59], v[156:159], v[180:183], v[56:59]
	v_mfma_f32_16x16x32_bf16 v[44:47], v[140:143], v[188:191], v[44:47]
	v_mfma_f32_16x16x32_bf16 v[40:43], v[156:159], v[188:191], v[40:43]
	v_mfma_f32_16x16x32_bf16 v[28:31], v[140:143], v[196:199], v[28:31]
	v_mfma_f32_16x16x32_bf16 v[24:27], v[156:159], v[196:199], v[24:27]
	v_mfma_f32_16x16x32_bf16 v[12:15], v[140:143], v[204:207], v[12:15]
	v_mfma_f32_16x16x32_bf16 v[8:11], v[156:159], v[204:207], v[8:11]
	v_mfma_f32_16x16x32_bf16 v[60:63], v[152:155], v[184:187], v[60:63]
	v_mfma_f32_16x16x32_bf16 v[56:59], v[160:163], v[184:187], v[56:59]
	v_mfma_f32_16x16x32_bf16 v[44:47], v[152:155], v[192:195], v[44:47]
	v_mfma_f32_16x16x32_bf16 v[40:43], v[160:163], v[192:195], v[40:43]
	v_mfma_f32_16x16x32_bf16 v[28:31], v[152:155], v[200:203], v[28:31]
	v_mfma_f32_16x16x32_bf16 v[24:27], v[160:163], v[200:203], v[24:27]
	v_mfma_f32_16x16x32_bf16 v[12:15], v[152:155], v[208:211], v[12:15]
	v_mfma_f32_16x16x32_bf16 v[8:11], v[160:163], v[208:211], v[8:11]
	v_mfma_f32_16x16x32_bf16 v[52:55], v[164:167], v[180:183], v[52:55]
	v_mfma_f32_16x16x32_bf16 v[48:51], v[172:175], v[180:183], v[48:51]
	v_mfma_f32_16x16x32_bf16 v[36:39], v[164:167], v[188:191], v[36:39]
	v_mfma_f32_16x16x32_bf16 v[32:35], v[172:175], v[188:191], v[32:35]
	v_mfma_f32_16x16x32_bf16 v[20:23], v[164:167], v[196:199], v[20:23]
	v_mfma_f32_16x16x32_bf16 v[16:19], v[172:175], v[196:199], v[16:19]
	v_mfma_f32_16x16x32_bf16 v[4:7], v[164:167], v[204:207], v[4:7]
	v_mfma_f32_16x16x32_bf16 v[0:3], v[172:175], v[204:207], v[0:3]
	v_mfma_f32_16x16x32_bf16 v[52:55], v[168:171], v[184:187], v[52:55]
	v_mfma_f32_16x16x32_bf16 v[48:51], v[176:179], v[184:187], v[48:51]
	v_mfma_f32_16x16x32_bf16 v[36:39], v[168:171], v[192:195], v[36:39]
	v_mfma_f32_16x16x32_bf16 v[32:35], v[176:179], v[192:195], v[32:35]
	v_mfma_f32_16x16x32_bf16 v[20:23], v[168:171], v[200:203], v[20:23]
	v_mfma_f32_16x16x32_bf16 v[16:19], v[176:179], v[200:203], v[16:19]
	v_mfma_f32_16x16x32_bf16 v[4:7], v[168:171], v[208:211], v[4:7]
	v_mfma_f32_16x16x32_bf16 v[0:3], v[176:179], v[208:211], v[0:3]
	s_setprio 0
	s_barrier
	s_add_i32 s61, s61, 2
	s_add_u32 s22, s22, 0x100
	s_addc_u32 s23, s23, 0
	s_add_u32 s8, s8, 0x100
	s_addc_u32 s9, s9, 0
	s_cmpk_gt_u32 s61, 0x55
	s_cbranch_scc0 .LBB0_1513
	s_and_b64 vcc, exec, s[14:15]
	s_cbranch_vccz .LBB0_1516
	s_barrier
